# tile-loop exits: dropped the full vmcnt(0) before the sample GEMM (the LDS-DMA prefetches it guarded are older than the epilogue's own full wait); plus skip-first-two-waits in all 8 GEMM phases
# speedup vs baseline: 1.0057x; 1.0057x over previous
; #define PG8_WAIT_V(n) asm volatile("s_waitcnt vmcnt(" #n ")" ::: "memory")
; #define PG8_BAR __builtin_amdgcn_s_barrier()
; template <class Epi, bool ALIGN_EPI>
; __device__ __forceinline__ void gemm_phase(LAS unsigned char* lds, const Gemm g, const StaticOrder& S, const Epi& E) {
;     ...
;     PG8_WAIT_V(0);
;     if constexpr (!ALIGN_EPI) { if (wr == 0) PG8_BAR; }
;     PG8_BAR;
.LBB0_335:
	v_readlane_b32 s72, v247, 5
	v_readlane_b32 s73, v247, 6
	s_barrier

; #define LAS __attribute__((address_space(3)))
; #define PG8_WAIT_V(n) asm volatile("s_waitcnt vmcnt(" #n ")" ::: "memory")
; #define PG8_BAR __builtin_amdgcn_s_barrier()
; template <class Epi, bool ALIGN_EPI>
; __device__ __forceinline__ void gemm_phase(LAS unsigned char* lds, const Gemm g, const StaticOrder& S, const Epi& E) {
;     ...
;         cur = nxt; cA = nA; cB = nB; ++ui;
;         if constexpr (ALIGN_EPI) { if (wr == 1) PG8_BAR; }
;     }
;     PG8_WAIT_V(0);
;     if constexpr (!ALIGN_EPI) { if (wr == 0) PG8_BAR; }
;     PG8_BAR;
; template <class EpiS>
; DI void sample_gemm(LAS unsigned char* lds, const bf16_t* A, const bf16_t* Bt, int nN, int K, const EpiS& E) {
;     const int tid = threadIdx.x, lane = tid & 63, w = __builtin_amdgcn_readfirstlane(tid >> 6), r32 = lane & 31, h = lane >> 5;
;     const int nunits = 16 * nN, kw = K >> 3, nk = kw >> 4;
;     for (int un = (int)blockIdx.x; un < nunits; un += (int)gridDim.x) {
;         const int rb = un & 3, wc = (un >> 2) & 3, pn = un >> 4;
;         const bf16_t* ap = A + (size_t)(MP + rb * 32 + r32) * K + w * kw + h * 8;
;         const bf16_t* b0p = Bt + (size_t)(pn * 256 + wc * 32 + r32) * K + w * kw + h * 8;
;         const bf16_t* b1p = b0p + (size_t)128 * K;
;         f32x16 c0, c1;
; #pragma unroll
;         for (int r = 0; r < 16; ++r) { c0[r] = 0.f; c1[r] = 0.f; }
; #pragma unroll 8
;         for (int ks = 0; ks < nk; ++ks) {
;             const bf16x8 a = *(const bf16x8*)(ap + ks * 16), b0 = *(const bf16x8*)(b0p + ks * 16), b1 = *(const bf16x8*)(b1p + ks * 16);
;             c0 = __builtin_amdgcn_mfma_f32_32x32x16_bf16(a, b0, c0, 0, 0, 0);
;             c1 = __builtin_amdgcn_mfma_f32_32x32x16_bf16(a, b1, c1, 0, 0, 0);
;         }
;         __syncthreads();
;         LAS float* part = (LAS float*)(lds + w * 8192);
; #pragma unroll
;         for (int r = 0; r < 16; ++r) { const int row = (r & 3) + 8 * (r >> 2) + 4 * h; part[row * 64 + r32] = c0[r]; part[row * 64 + 32 + r32] = c1[r]; }
;         __syncthreads();
;         f32x4 v = (f32x4){0.f, 0.f, 0.f, 0.f};
; #pragma unroll
;         for (int ww = 0; ww < 8; ++ww) v += *(const LAS f32x4*)(lds + ww * 8192 + (tid >> 4) * 256 + (tid & 15) * 16);
.LBB0_539:
	s_or_b64 exec, exec, s[60:61]
	s_andn2_b64 vcc, exec, s[4:5]
	s_mov_b64 s[4:5], -1
	s_cbranch_vccnz .LBB0_512
	s_andn2_b64 vcc, exec, s[16:17]
	s_cbranch_vccnz .LBB0_511
	s_barrier
	s_branch .LBB0_511
.LBB0_542:
	s_barrier
.LBB0_543:
	s_cmp_gt_i32 s2, 63
	v_readfirstlane_b32 s0, v206
	s_cbranch_scc1 .LBB0_548
	v_and_b32_e32 v155, 63, v206
	v_lshrrev_b32_e32 v156, 6, v206
	v_and_b32_e32 v156, 7, v156
	v_lshlrev_b32_e32 v156, 13, v156
	v_add_u32_e32 v156, 0x10000, v156
	v_lshrrev_b32_e32 v182, 3, v155
	v_and_b32_e32 v165, 31, v155
	v_sub_u32_e32 v182, v182, v165
	v_lshlrev_b32_e32 v182, 11, v182
	v_and_b32_e32 v165, 7, v155
	v_lshrrev_b32_e32 v183, 5, v155
	v_sub_u32_e32 v165, v165, v183
	v_lshl_add_u32 v182, v165, 4, v182
	v_ashrrev_i32_e32 v183, 31, v182
	v_lshrrev_b32_e32 v194, 4, v155
	v_and_b32_e32 v194, 3, v194
	v_and_b32_e32 v165, 7, v155
	v_xor_b32_e32 v194, v194, v165
	v_lshlrev_b32_e32 v194, 4, v194
	v_lshrrev_b32_e32 v165, 3, v155
	v_lshl_add_u32 v194, v165, 7, v194
	v_add_u32_e32 v194, v156, v194
	v_xor_b32_e32 v195, 64, v194
	v_and_b32_e32 v165, 31, v155
	v_lshl_add_u32 v156, v165, 7, v156
	v_lshrrev_b32_e32 v165, 1, v155
	v_and_b32_e32 v165, 7, v165
	v_lshrrev_b32_e32 v155, 5, v155
	v_add_u32_e32 v244, 0, v155
	v_xor_b32_e32 v244, v244, v165
	v_lshl_add_u32 v244, v244, 4, v156
	v_add_u32_e32 v245, 2, v155
	v_xor_b32_e32 v245, v245, v165
	v_lshl_add_u32 v245, v245, 4, v156
	v_add_u32_e32 v246, 4, v155
	v_xor_b32_e32 v246, v246, v165
	v_lshl_add_u32 v246, v246, 4, v156
	v_add_u32_e32 v193, 6, v155
	v_xor_b32_e32 v193, v193, v165
	v_lshl_add_u32 v193, v193, 4, v156
	s_mov_b32 s80, 0x4000
	s_mov_b32 s81, 0
	s_mov_b32 s82, 0xffff4000
	s_mov_b32 s83, -1
	s_and_b32 s76, s2, 0xffffffe0
	s_and_b32 s77, s2, 7
	s_lshl_b32 s77, s77, 2
	s_or_b32 s76, s76, s77
	s_bfe_u32 s77, s2, 0x20003
	s_or_b32 s76, s76, s77
	s_and_b32 s77, s3, 31
	s_cmp_eq_u32 s77, 0
	s_cselect_b32 s76, s76, s2
	v_and_b32_e32 v6, 1, v210
	v_lshlrev_b32_e32 v34, 4, v6
	v_mov_b32_e32 v35, 0
	s_add_u32 s4, s14, 0xf8000000
	v_lshl_add_u64 v[4:5], s[10:11], 0, v[34:35]
	v_and_b32_e32 v9, 28, v209
	s_movk_i32 s10, 0x80
	s_addc_u32 s5, s15, -1
	v_and_or_b32 v41, v207, s10, v9
	s_lshr_b32 s10, s0, 6
	s_mov_b32 s1, 0
	s_waitcnt lgkmcnt(0)
	v_lshl_add_u64 v[2:3], s[26:27], 0, v[34:35]
	s_lshl_b32 s0, s10, 8
	v_lshl_add_u64 v[36:37], v[2:3], 0, s[0:1]
	v_mbcnt_lo_u32_b32 v2, -1, 0
	v_mbcnt_hi_u32_b32 v2, -1, v2
	v_lshl_add_u64 v[38:39], v[4:5], 0, s[0:1]
	v_and_b32_e32 v4, 64, v2
	v_xor_b32_e32 v3, 1, v2
	v_add_u32_e32 v4, 64, v4
	v_cmp_lt_i32_e64 s[0:1], v3, v4
	v_and_b32_e32 v40, 31, v206
	v_lshlrev_b32_e32 v6, 10, v6
	v_cndmask_b32_e64 v3, v2, v3, s[0:1]
	v_lshlrev_b32_e32 v42, 2, v3
	v_xor_b32_e32 v3, 2, v2
	v_cmp_lt_i32_e64 s[0:1], v3, v4
	v_lshlrev_b32_e32 v7, 2, v40
	v_add3_u32 v6, 0, v6, v7
	v_cndmask_b32_e64 v3, v2, v3, s[0:1]
	v_lshlrev_b32_e32 v43, 2, v3
	v_xor_b32_e32 v3, 4, v2
	v_cmp_lt_i32_e64 s[0:1], v3, v4
	v_and_b32_e32 v7, 0x3f00, v207
	s_lshl_b32 s17, s10, 13
	v_cndmask_b32_e64 v3, v2, v3, s[0:1]
	v_lshlrev_b32_e32 v44, 2, v3
	v_xor_b32_e32 v3, 8, v2
	v_cmp_lt_i32_e64 s[0:1], v3, v4
	v_add_u32_e32 v7, 0, v7
	v_and_b32_e32 v8, 0xf0, v207
	v_cndmask_b32_e64 v2, v2, v3, s[0:1]
	v_add_u32_e32 v46, s17, v6
	v_cmp_eq_u32_e32 vcc, 0, v208
	v_lshlrev_b32_e32 v45, 2, v2
	s_lshl_b32 s10, s76, 3
	s_lshl_b32 s11, s3, 3
	s_lshl_b32 s12, s76, 4
	s_lshl_b32 s13, s3, 4
	s_lshl_b32 s14, s76, 5
	s_lshl_b32 s15, s3, 5
	s_mov_b32 s16, 0x40000
	v_add_u32_e32 v47, v7, v8
	v_add_u32_e32 v48, 0x800, v46
	v_add_u32_e32 v49, 0x1000, v46
	v_add_u32_e32 v50, 0x1800, v46
	s_mov_b32 s17, s76
	s_branch .LBB0_546

; DI u32x4 pk8(f32x4 a, f32x4 b) { u32x4 w; w.x = pk2(a[0], a[1]); w.y = pk2(a[2], a[3]); w.z = pk2(b[0], b[1]); w.w = pk2(b[2], b[3]); return w; }
; DI float row_rstd(const float* SS, int row) { return rsqrtf(SS[row] * (1.0f / 1024.0f) + 1e-6f); }
;     DI void operator()(const Acc& acc, const pg8::Unit& u, int wr, int wc, int fr, int fq) const {
;         const int colb = u.pn * 128 + wc * 32 + fq * 8;
;         float rsv[2][4];
; #pragma unroll
;         for (int ai = 0; ai < 2; ++ai)
; #pragma unroll
;             for (int m = 0; m < 4; ++m) rsv[ai][m] = row_rstd(SS, u.pm * 256 + ai * 128 + wr * 64 + m * 16 + fr);
; #pragma unroll
;         for (int ai = 0; ai < 2; ++ai)
; #pragma unroll
;             for (int m = 0; m < 4; ++m) {
;                 const int row = u.pm * 256 + ai * 128 + wr * 64 + m * 16 + fr;
;                 const float rs = rsv[ai][m];
;                 f32x4 h0, h1;
;                 const float rs2 = rs * rs, nrl = -rs * LOG2E;
; #pragma unroll
;                 for (int i = 0; i < 4; ++i) {
;                     const float a0 = acc[ai][0][m][0][i], a1 = acc[ai][0][m][1][i];
;                     h0[i] = (a0 * acc[ai][1][m][0][i]) * rs2 * __builtin_amdgcn_rcpf(1.0f + __builtin_amdgcn_exp2f(a0 * nrl));
;                     h1[i] = (a1 * acc[ai][1][m][1][i]) * rs2 * __builtin_amdgcn_rcpf(1.0f + __builtin_amdgcn_exp2f(a1 * nrl));
;                 }
;                 __builtin_nontemporal_store(pk8(h0, h1), (u32x4*)(HID + (size_t)row * FH + colb));
;             }
.LBB0_612:
	v_lshl_add_u32 v160, s4, 8, v165
	v_lshlrev_b32_e32 v185, 2, v160
	global_load_dword v146, v185, s[50:51]
	global_load_dword v147, v185, s[50:51] offset:64
	global_load_dword v148, v185, s[50:51] offset:128
	global_load_dword v149, v185, s[50:51] offset:192
	global_load_dword v150, v185, s[50:51] offset:512
	global_load_dword v151, v185, s[50:51] offset:576
	global_load_dword v152, v185, s[50:51] offset:640
	global_load_dword v153, v185, s[50:51] offset:704
	v_lshl_or_b32 v181, s5, 7, v167
	v_lshlrev_b32_e32 v181, 1, v181
	v_mad_u32_u24 v183, v160, s83, v181
	v_pk_mul_f32 v[122:123], v[126:127], v[122:123]
	v_pk_mul_f32 v[124:125], v[128:129], v[124:125]
	v_pk_mul_f32 v[114:115], v[118:119], v[114:115]
	v_pk_mul_f32 v[116:117], v[120:121], v[116:117]
	v_pk_mul_f32 v[106:107], v[110:111], v[106:107]
	v_pk_mul_f32 v[108:109], v[112:113], v[108:109]
	v_pk_mul_f32 v[98:99], v[102:103], v[98:99]
	v_pk_mul_f32 v[100:101], v[104:105], v[100:101]
	v_pk_mul_f32 v[90:91], v[94:95], v[90:91]
	v_pk_mul_f32 v[92:93], v[96:97], v[92:93]
	v_pk_mul_f32 v[82:83], v[86:87], v[82:83]
	v_pk_mul_f32 v[84:85], v[88:89], v[84:85]
	v_pk_mul_f32 v[74:75], v[78:79], v[74:75]
	v_pk_mul_f32 v[76:77], v[80:81], v[76:77]
	v_pk_mul_f32 v[66:67], v[70:71], v[66:67]
	v_pk_mul_f32 v[68:69], v[72:73], v[68:69]
	v_pk_mul_f32 v[58:59], v[62:63], v[58:59]
	v_pk_mul_f32 v[60:61], v[64:65], v[60:61]
	v_pk_mul_f32 v[50:51], v[54:55], v[50:51]
	v_pk_mul_f32 v[52:53], v[56:57], v[52:53]
	v_pk_mul_f32 v[42:43], v[46:47], v[42:43]
	v_pk_mul_f32 v[44:45], v[48:49], v[44:45]
	v_pk_mul_f32 v[34:35], v[38:39], v[34:35]
	v_pk_mul_f32 v[36:37], v[40:41], v[36:37]
	v_pk_mul_f32 v[26:27], v[30:31], v[26:27]
	v_pk_mul_f32 v[28:29], v[32:33], v[28:29]
	v_pk_mul_f32 v[18:19], v[22:23], v[18:19]
	v_pk_mul_f32 v[20:21], v[24:25], v[20:21]
	v_pk_mul_f32 v[10:11], v[14:15], v[10:11]
	v_pk_mul_f32 v[12:13], v[16:17], v[12:13]
	v_pk_mul_f32 v[2:3], v[6:7], v[2:3]
	v_pk_mul_f32 v[4:5], v[8:9], v[4:5]
	s_andn2_b64 vcc, exec, s[0:1]
	s_mov_b64 s[0:1], -1
	s_waitcnt vmcnt(0)
	v_fmamk_f32 v232, v146, 0x3a800000, v171
	v_fmamk_f32 v234, v147, 0x3a800000, v171
	v_fmamk_f32 v236, v148, 0x3a800000, v171
	v_fmamk_f32 v238, v149, 0x3a800000, v171
	v_fmamk_f32 v240, v150, 0x3a800000, v171
	v_fmamk_f32 v242, v151, 0x3a800000, v171
	v_fmamk_f32 v244, v152, 0x3a800000, v171
	v_fmamk_f32 v246, v153, 0x3a800000, v171
	v_rsq_f32_e32 v154, v232
	v_rsq_f32_e32 v155, v234
	v_rsq_f32_e32 v156, v236
	v_rsq_f32_e32 v157, v238
	v_rsq_f32_e32 v158, v240
	v_rsq_f32_e32 v159, v242
	v_rsq_f32_e32 v160, v244
	v_rsq_f32_e32 v161, v246
	v_mul_f32_e32 v172, 0xbfb8aa3b, v154
	v_mul_f32_e32 v174, 0xbfb8aa3b, v155
	v_mul_f32_e32 v176, 0xbfb8aa3b, v156
	v_mul_f32_e32 v178, 0xbfb8aa3b, v157
	v_mul_f32_e32 v180, 0xbfb8aa3b, v158
	v_mul_f32_e32 v182, 0xbfb8aa3b, v159
	v_mul_f32_e32 v184, 0xbfb8aa3b, v160
	v_mul_f32_e32 v230, 0xbfb8aa3b, v161
	v_pk_mul_f32 v[126:127], v[126:127], v[172:173] op_sel_hi:[1,0]
	v_pk_mul_f32 v[128:129], v[128:129], v[172:173] op_sel_hi:[1,0]
	v_pk_mul_f32 v[118:119], v[118:119], v[172:173] op_sel_hi:[1,0]
	v_pk_mul_f32 v[120:121], v[120:121], v[172:173] op_sel_hi:[1,0]
	v_exp_f32_e32 v126, v126
	v_exp_f32_e32 v127, v127
	v_exp_f32_e32 v128, v128
	v_exp_f32_e32 v129, v129
	v_exp_f32_e32 v118, v118
	v_exp_f32_e32 v119, v119
	v_exp_f32_e32 v120, v120
	v_exp_f32_e32 v121, v121
	v_pk_fma_f32 v[126:127], v[126:127], v[232:233], v[232:233] op_sel_hi:[1,0,0]
	v_pk_fma_f32 v[128:129], v[128:129], v[232:233], v[232:233] op_sel_hi:[1,0,0]
	v_pk_fma_f32 v[118:119], v[118:119], v[232:233], v[232:233] op_sel_hi:[1,0,0]
	v_pk_fma_f32 v[120:121], v[120:121], v[232:233], v[232:233] op_sel_hi:[1,0,0]
	v_rcp_f32_e32 v126, v126
	v_rcp_f32_e32 v127, v127
	v_rcp_f32_e32 v128, v128
	v_rcp_f32_e32 v129, v129
	v_rcp_f32_e32 v118, v118
	v_rcp_f32_e32 v119, v119
	v_rcp_f32_e32 v120, v120
	v_rcp_f32_e32 v121, v121
	v_pk_mul_f32 v[122:123], v[122:123], v[126:127]
	v_pk_mul_f32 v[124:125], v[124:125], v[128:129]
	v_pk_mul_f32 v[114:115], v[114:115], v[118:119]
	v_pk_mul_f32 v[116:117], v[116:117], v[120:121]
	v_cvt_pk_bf16_f32 v122, v122, v123
	v_cvt_pk_bf16_f32 v123, v124, v125
	v_cvt_pk_bf16_f32 v124, v114, v115
	v_cvt_pk_bf16_f32 v125, v116, v117
	global_store_dwordx4 v183, v[122:125], s[24:25] nt
	v_add_u32_e32 v183, 0x16000, v183
	v_pk_mul_f32 v[110:111], v[110:111], v[174:175] op_sel_hi:[1,0]
	v_pk_mul_f32 v[112:113], v[112:113], v[174:175] op_sel_hi:[1,0]
	v_pk_mul_f32 v[102:103], v[102:103], v[174:175] op_sel_hi:[1,0]
	v_pk_mul_f32 v[104:105], v[104:105], v[174:175] op_sel_hi:[1,0]
	v_exp_f32_e32 v110, v110
	v_exp_f32_e32 v111, v111
	v_exp_f32_e32 v112, v112
	v_exp_f32_e32 v113, v113
	v_exp_f32_e32 v102, v102
	v_exp_f32_e32 v103, v103
	v_exp_f32_e32 v104, v104
	v_exp_f32_e32 v105, v105
	v_pk_fma_f32 v[110:111], v[110:111], v[234:235], v[234:235] op_sel_hi:[1,0,0]
	v_pk_fma_f32 v[112:113], v[112:113], v[234:235], v[234:235] op_sel_hi:[1,0,0]
	v_pk_fma_f32 v[102:103], v[102:103], v[234:235], v[234:235] op_sel_hi:[1,0,0]
	v_pk_fma_f32 v[104:105], v[104:105], v[234:235], v[234:235] op_sel_hi:[1,0,0]
	v_rcp_f32_e32 v110, v110
	v_rcp_f32_e32 v111, v111
	v_rcp_f32_e32 v112, v112
	v_rcp_f32_e32 v113, v113
	v_rcp_f32_e32 v102, v102
	v_rcp_f32_e32 v103, v103
	v_rcp_f32_e32 v104, v104
	v_rcp_f32_e32 v105, v105
	v_pk_mul_f32 v[106:107], v[106:107], v[110:111]
	v_pk_mul_f32 v[108:109], v[108:109], v[112:113]
	v_pk_mul_f32 v[98:99], v[98:99], v[102:103]
	v_pk_mul_f32 v[100:101], v[100:101], v[104:105]
	v_cvt_pk_bf16_f32 v106, v106, v107
	v_cvt_pk_bf16_f32 v107, v108, v109
	v_cvt_pk_bf16_f32 v108, v98, v99
	v_cvt_pk_bf16_f32 v109, v100, v101
; DI u32x4 pk8(f32x4 a, f32x4 b) { u32x4 w; w.x = pk2(a[0], a[1]); w.y = pk2(a[2], a[3]); w.z = pk2(b[0], b[1]); w.w = pk2(b[2], b[3]); return w; }
;     DI void operator()(const Acc& acc, const pg8::Unit& u, int wr, int wc, int fr, int fq) const {
;     ...
; #pragma unroll
;                 for (int i = 0; i < 4; ++i) {
;                     const float a0 = acc[ai][0][m][0][i], a1 = acc[ai][0][m][1][i];
;                     h0[i] = (a0 * acc[ai][1][m][0][i]) * rs2 * __builtin_amdgcn_rcpf(1.0f + __builtin_amdgcn_exp2f(a0 * nrl));
;                     h1[i] = (a1 * acc[ai][1][m][1][i]) * rs2 * __builtin_amdgcn_rcpf(1.0f + __builtin_amdgcn_exp2f(a1 * nrl));
;                 }
;                 __builtin_nontemporal_store(pk8(h0, h1), (u32x4*)(HID + (size_t)row * FH + colb));
	global_store_dwordx4 v183, v[106:109], s[24:25] nt
	v_add_u32_e32 v183, 0x16000, v183
	v_pk_mul_f32 v[94:95], v[94:95], v[176:177] op_sel_hi:[1,0]
	v_pk_mul_f32 v[96:97], v[96:97], v[176:177] op_sel_hi:[1,0]
	v_pk_mul_f32 v[86:87], v[86:87], v[176:177] op_sel_hi:[1,0]
	v_pk_mul_f32 v[88:89], v[88:89], v[176:177] op_sel_hi:[1,0]
	v_exp_f32_e32 v94, v94
	v_exp_f32_e32 v95, v95
	v_exp_f32_e32 v96, v96
	v_exp_f32_e32 v97, v97
	v_exp_f32_e32 v86, v86
	v_exp_f32_e32 v87, v87
	v_exp_f32_e32 v88, v88
	v_exp_f32_e32 v89, v89
	v_pk_fma_f32 v[94:95], v[94:95], v[236:237], v[236:237] op_sel_hi:[1,0,0]
	v_pk_fma_f32 v[96:97], v[96:97], v[236:237], v[236:237] op_sel_hi:[1,0,0]
	v_pk_fma_f32 v[86:87], v[86:87], v[236:237], v[236:237] op_sel_hi:[1,0,0]
	v_pk_fma_f32 v[88:89], v[88:89], v[236:237], v[236:237] op_sel_hi:[1,0,0]
	v_rcp_f32_e32 v94, v94
	v_rcp_f32_e32 v95, v95
	v_rcp_f32_e32 v96, v96
	v_rcp_f32_e32 v97, v97
	v_rcp_f32_e32 v86, v86
	v_rcp_f32_e32 v87, v87
	v_rcp_f32_e32 v88, v88
	v_rcp_f32_e32 v89, v89
	v_pk_mul_f32 v[90:91], v[90:91], v[94:95]
	v_pk_mul_f32 v[92:93], v[92:93], v[96:97]
	v_pk_mul_f32 v[82:83], v[82:83], v[86:87]
	v_pk_mul_f32 v[84:85], v[84:85], v[88:89]
	v_cvt_pk_bf16_f32 v90, v90, v91
	v_cvt_pk_bf16_f32 v91, v92, v93
	v_cvt_pk_bf16_f32 v92, v82, v83
	v_cvt_pk_bf16_f32 v93, v84, v85
	global_store_dwordx4 v183, v[90:93], s[24:25] nt
	v_add_u32_e32 v183, 0x16000, v183
	v_pk_mul_f32 v[78:79], v[78:79], v[178:179] op_sel_hi:[1,0]
	v_pk_mul_f32 v[80:81], v[80:81], v[178:179] op_sel_hi:[1,0]
	v_pk_mul_f32 v[70:71], v[70:71], v[178:179] op_sel_hi:[1,0]
	v_pk_mul_f32 v[72:73], v[72:73], v[178:179] op_sel_hi:[1,0]
	v_exp_f32_e32 v78, v78
	v_exp_f32_e32 v79, v79
	v_exp_f32_e32 v80, v80
	v_exp_f32_e32 v81, v81
	v_exp_f32_e32 v70, v70
	v_exp_f32_e32 v71, v71
	v_exp_f32_e32 v72, v72
	v_exp_f32_e32 v73, v73
	v_pk_fma_f32 v[78:79], v[78:79], v[238:239], v[238:239] op_sel_hi:[1,0,0]
	v_pk_fma_f32 v[80:81], v[80:81], v[238:239], v[238:239] op_sel_hi:[1,0,0]
	v_pk_fma_f32 v[70:71], v[70:71], v[238:239], v[238:239] op_sel_hi:[1,0,0]
	v_pk_fma_f32 v[72:73], v[72:73], v[238:239], v[238:239] op_sel_hi:[1,0,0]
	v_rcp_f32_e32 v78, v78
	v_rcp_f32_e32 v79, v79
	v_rcp_f32_e32 v80, v80
	v_rcp_f32_e32 v81, v81
	v_rcp_f32_e32 v70, v70
	v_rcp_f32_e32 v71, v71
	v_rcp_f32_e32 v72, v72
	v_rcp_f32_e32 v73, v73
	v_pk_mul_f32 v[74:75], v[74:75], v[78:79]
	v_pk_mul_f32 v[76:77], v[76:77], v[80:81]
	v_pk_mul_f32 v[66:67], v[66:67], v[70:71]
	v_pk_mul_f32 v[68:69], v[68:69], v[72:73]
	v_cvt_pk_bf16_f32 v74, v74, v75
	v_cvt_pk_bf16_f32 v75, v76, v77
	v_cvt_pk_bf16_f32 v76, v66, v67
	v_cvt_pk_bf16_f32 v77, v68, v69
	global_store_dwordx4 v183, v[74:77], s[24:25] nt
	v_add_u32_e32 v183, 0x6e000, v183
	v_pk_mul_f32 v[62:63], v[62:63], v[180:181] op_sel_hi:[1,0]
	v_pk_mul_f32 v[64:65], v[64:65], v[180:181] op_sel_hi:[1,0]
	v_pk_mul_f32 v[54:55], v[54:55], v[180:181] op_sel_hi:[1,0]
	v_pk_mul_f32 v[56:57], v[56:57], v[180:181] op_sel_hi:[1,0]
	v_exp_f32_e32 v62, v62
	v_exp_f32_e32 v63, v63
	v_exp_f32_e32 v64, v64
	v_exp_f32_e32 v65, v65
	v_exp_f32_e32 v54, v54
	v_exp_f32_e32 v55, v55
	v_exp_f32_e32 v56, v56
	v_exp_f32_e32 v57, v57
	v_pk_fma_f32 v[62:63], v[62:63], v[240:241], v[240:241] op_sel_hi:[1,0,0]
	v_pk_fma_f32 v[64:65], v[64:65], v[240:241], v[240:241] op_sel_hi:[1,0,0]
	v_pk_fma_f32 v[54:55], v[54:55], v[240:241], v[240:241] op_sel_hi:[1,0,0]
	v_pk_fma_f32 v[56:57], v[56:57], v[240:241], v[240:241] op_sel_hi:[1,0,0]
	v_rcp_f32_e32 v62, v62
	v_rcp_f32_e32 v63, v63
	v_rcp_f32_e32 v64, v64
	v_rcp_f32_e32 v65, v65
	v_rcp_f32_e32 v54, v54
	v_rcp_f32_e32 v55, v55
	v_rcp_f32_e32 v56, v56
	v_rcp_f32_e32 v57, v57
	v_pk_mul_f32 v[58:59], v[58:59], v[62:63]
	v_pk_mul_f32 v[60:61], v[60:61], v[64:65]
	v_pk_mul_f32 v[50:51], v[50:51], v[54:55]
	v_pk_mul_f32 v[52:53], v[52:53], v[56:57]
	v_cvt_pk_bf16_f32 v58, v58, v59
	v_cvt_pk_bf16_f32 v59, v60, v61
	v_cvt_pk_bf16_f32 v60, v50, v51
	v_cvt_pk_bf16_f32 v61, v52, v53
	global_store_dwordx4 v183, v[58:61], s[24:25] nt
	v_add_u32_e32 v183, 0x16000, v183
	v_pk_mul_f32 v[46:47], v[46:47], v[182:183] op_sel_hi:[1,0]
	v_pk_mul_f32 v[48:49], v[48:49], v[182:183] op_sel_hi:[1,0]
	v_pk_mul_f32 v[38:39], v[38:39], v[182:183] op_sel_hi:[1,0]
	v_pk_mul_f32 v[40:41], v[40:41], v[182:183] op_sel_hi:[1,0]
	v_exp_f32_e32 v46, v46
	v_exp_f32_e32 v47, v47
	v_exp_f32_e32 v48, v48
	v_exp_f32_e32 v49, v49
	v_exp_f32_e32 v38, v38
	v_exp_f32_e32 v39, v39
	v_exp_f32_e32 v40, v40
	v_exp_f32_e32 v41, v41
	v_pk_fma_f32 v[46:47], v[46:47], v[242:243], v[242:243] op_sel_hi:[1,0,0]
	v_pk_fma_f32 v[48:49], v[48:49], v[242:243], v[242:243] op_sel_hi:[1,0,0]
	v_pk_fma_f32 v[38:39], v[38:39], v[242:243], v[242:243] op_sel_hi:[1,0,0]
	v_pk_fma_f32 v[40:41], v[40:41], v[242:243], v[242:243] op_sel_hi:[1,0,0]
	v_rcp_f32_e32 v46, v46
	v_rcp_f32_e32 v47, v47
	v_rcp_f32_e32 v48, v48
	v_rcp_f32_e32 v49, v49
	v_rcp_f32_e32 v38, v38
	v_rcp_f32_e32 v39, v39
	v_rcp_f32_e32 v40, v40
	v_rcp_f32_e32 v41, v41
	v_pk_mul_f32 v[42:43], v[42:43], v[46:47]
	v_pk_mul_f32 v[44:45], v[44:45], v[48:49]
	v_pk_mul_f32 v[34:35], v[34:35], v[38:39]
	v_pk_mul_f32 v[36:37], v[36:37], v[40:41]
	v_cvt_pk_bf16_f32 v42, v42, v43
	v_cvt_pk_bf16_f32 v43, v44, v45
	v_cvt_pk_bf16_f32 v44, v34, v35
	v_cvt_pk_bf16_f32 v45, v36, v37
	global_store_dwordx4 v183, v[42:45], s[24:25] nt
	v_add_u32_e32 v183, 0x16000, v183
	v_pk_mul_f32 v[30:31], v[30:31], v[184:185] op_sel_hi:[1,0]
	v_pk_mul_f32 v[32:33], v[32:33], v[184:185] op_sel_hi:[1,0]
	v_pk_mul_f32 v[22:23], v[22:23], v[184:185] op_sel_hi:[1,0]
; #define LAS __attribute__((address_space(3)))
; DI u32x4 pk8(f32x4 a, f32x4 b) { u32x4 w; w.x = pk2(a[0], a[1]); w.y = pk2(a[2], a[3]); w.z = pk2(b[0], b[1]); w.w = pk2(b[2], b[3]); return w; }
; #define PG8_WAIT_V(n) asm volatile("s_waitcnt vmcnt(" #n ")" ::: "memory")
; #define PG8_BAR __builtin_amdgcn_s_barrier()
; template <class Epi, bool ALIGN_EPI>
; __device__ __forceinline__ void gemm_phase(LAS unsigned char* lds, const Gemm g, const StaticOrder& S, const Epi& E) {
;     ...
;     PG8_WAIT_V(0);
;     if constexpr (!ALIGN_EPI) { if (wr == 0) PG8_BAR; }
;     PG8_BAR;
;     DI void operator()(const Acc& acc, const pg8::Unit& u, int wr, int wc, int fr, int fq) const {
;     ...
; #pragma unroll
;                 for (int i = 0; i < 4; ++i) {
;                     const float a0 = acc[ai][0][m][0][i], a1 = acc[ai][0][m][1][i];
;                     h0[i] = (a0 * acc[ai][1][m][0][i]) * rs2 * __builtin_amdgcn_rcpf(1.0f + __builtin_amdgcn_exp2f(a0 * nrl));
;                     h1[i] = (a1 * acc[ai][1][m][1][i]) * rs2 * __builtin_amdgcn_rcpf(1.0f + __builtin_amdgcn_exp2f(a1 * nrl));
;                 }
;                 __builtin_nontemporal_store(pk8(h0, h1), (u32x4*)(HID + (size_t)row * FH + colb));
; template <class EpiS>
; DI void sample_gemm(LAS unsigned char* lds, const bf16_t* A, const bf16_t* Bt, int nN, int K, const EpiS& E) {
;     const int tid = threadIdx.x, lane = tid & 63, w = __builtin_amdgcn_readfirstlane(tid >> 6), r32 = lane & 31, h = lane >> 5;
;     const int nunits = 16 * nN, kw = K >> 3, nk = kw >> 4;
;     for (int un = (int)blockIdx.x; un < nunits; un += (int)gridDim.x) {
;         const int rb = un & 3, wc = (un >> 2) & 3, pn = un >> 4;
;         const bf16_t* ap = A + (size_t)(MP + rb * 32 + r32) * K + w * kw + h * 8;
;         const bf16_t* b0p = Bt + (size_t)(pn * 256 + wc * 32 + r32) * K + w * kw + h * 8;
;         const bf16_t* b1p = b0p + (size_t)128 * K;
	v_pk_mul_f32 v[24:25], v[24:25], v[184:185] op_sel_hi:[1,0]
	v_exp_f32_e32 v30, v30
	v_exp_f32_e32 v31, v31
	v_exp_f32_e32 v32, v32
	v_exp_f32_e32 v33, v33
	v_exp_f32_e32 v22, v22
	v_exp_f32_e32 v23, v23
	v_exp_f32_e32 v24, v24
	v_exp_f32_e32 v25, v25
	v_pk_fma_f32 v[30:31], v[30:31], v[244:245], v[244:245] op_sel_hi:[1,0,0]
	v_pk_fma_f32 v[32:33], v[32:33], v[244:245], v[244:245] op_sel_hi:[1,0,0]
	v_pk_fma_f32 v[22:23], v[22:23], v[244:245], v[244:245] op_sel_hi:[1,0,0]
	v_pk_fma_f32 v[24:25], v[24:25], v[244:245], v[244:245] op_sel_hi:[1,0,0]
	v_rcp_f32_e32 v30, v30
	v_rcp_f32_e32 v31, v31
	v_rcp_f32_e32 v32, v32
	v_rcp_f32_e32 v33, v33
	v_rcp_f32_e32 v22, v22
	v_rcp_f32_e32 v23, v23
	v_rcp_f32_e32 v24, v24
	v_rcp_f32_e32 v25, v25
	v_pk_mul_f32 v[26:27], v[26:27], v[30:31]
	v_pk_mul_f32 v[28:29], v[28:29], v[32:33]
	v_pk_mul_f32 v[18:19], v[18:19], v[22:23]
	v_pk_mul_f32 v[20:21], v[20:21], v[24:25]
	v_cvt_pk_bf16_f32 v26, v26, v27
	v_cvt_pk_bf16_f32 v27, v28, v29
	v_cvt_pk_bf16_f32 v28, v18, v19
	v_cvt_pk_bf16_f32 v29, v20, v21
	global_store_dwordx4 v183, v[26:29], s[24:25] nt
	v_add_u32_e32 v183, 0x16000, v183
	v_pk_mul_f32 v[14:15], v[14:15], v[230:231] op_sel_hi:[1,0]
	v_pk_mul_f32 v[16:17], v[16:17], v[230:231] op_sel_hi:[1,0]
	v_pk_mul_f32 v[6:7], v[6:7], v[230:231] op_sel_hi:[1,0]
	v_pk_mul_f32 v[8:9], v[8:9], v[230:231] op_sel_hi:[1,0]
	v_exp_f32_e32 v14, v14
	v_exp_f32_e32 v15, v15
	v_exp_f32_e32 v16, v16
	v_exp_f32_e32 v17, v17
	v_exp_f32_e32 v6, v6
	v_exp_f32_e32 v7, v7
	v_exp_f32_e32 v8, v8
	v_exp_f32_e32 v9, v9
	v_pk_fma_f32 v[14:15], v[14:15], v[246:247], v[246:247] op_sel_hi:[1,0,0]
	v_pk_fma_f32 v[16:17], v[16:17], v[246:247], v[246:247] op_sel_hi:[1,0,0]
	v_pk_fma_f32 v[6:7], v[6:7], v[246:247], v[246:247] op_sel_hi:[1,0,0]
	v_pk_fma_f32 v[8:9], v[8:9], v[246:247], v[246:247] op_sel_hi:[1,0,0]
	v_rcp_f32_e32 v14, v14
	v_rcp_f32_e32 v15, v15
	v_rcp_f32_e32 v16, v16
	v_rcp_f32_e32 v17, v17
	v_rcp_f32_e32 v6, v6
	v_rcp_f32_e32 v7, v7
	v_rcp_f32_e32 v8, v8
	v_rcp_f32_e32 v9, v9
	v_pk_mul_f32 v[10:11], v[10:11], v[14:15]
	v_pk_mul_f32 v[12:13], v[12:13], v[16:17]
	v_pk_mul_f32 v[2:3], v[2:3], v[6:7]
	v_pk_mul_f32 v[4:5], v[4:5], v[8:9]
	v_cvt_pk_bf16_f32 v10, v10, v11
	v_cvt_pk_bf16_f32 v11, v12, v13
	v_cvt_pk_bf16_f32 v12, v2, v3
	v_cvt_pk_bf16_f32 v13, v4, v5
	global_store_dwordx4 v183, v[10:13], s[24:25] nt
	s_cbranch_vccnz .LBB0_605
	s_andn2_b64 vcc, exec, s[54:55]
	s_cbranch_vccnz .LBB0_604
	s_barrier
	s_branch .LBB0_604
.LBB0_615:
	s_barrier
.LBB0_616:
	s_cmpk_gt_i32 s2, 0x15f
	v_readfirstlane_b32 s0, v162
	s_cbranch_scc1 .LBB0_621
	v_and_b32_e32 v155, 63, v162
	v_lshrrev_b32_e32 v156, 6, v162
	v_and_b32_e32 v156, 7, v156
	v_lshlrev_b32_e32 v156, 13, v156
	v_add_u32_e32 v156, 0x10000, v156
	v_lshrrev_b32_e32 v182, 3, v155
	v_and_b32_e32 v165, 31, v155
	v_sub_u32_e32 v182, v182, v165
	v_lshlrev_b32_e32 v182, 11, v182
	v_and_b32_e32 v165, 7, v155
	v_lshrrev_b32_e32 v183, 5, v155
	v_sub_u32_e32 v165, v165, v183
	v_lshl_add_u32 v182, v165, 4, v182
	v_ashrrev_i32_e32 v183, 31, v182
	v_lshrrev_b32_e32 v194, 4, v155
	v_and_b32_e32 v194, 3, v194
	v_and_b32_e32 v165, 7, v155
	v_xor_b32_e32 v194, v194, v165
	v_lshlrev_b32_e32 v194, 4, v194
	v_lshrrev_b32_e32 v165, 3, v155
	v_lshl_add_u32 v194, v165, 7, v194
	v_add_u32_e32 v194, v156, v194
	v_xor_b32_e32 v195, 64, v194
	v_and_b32_e32 v165, 31, v155
	v_lshl_add_u32 v156, v165, 7, v156
	v_lshrrev_b32_e32 v165, 1, v155
	v_and_b32_e32 v165, 7, v165
	v_lshrrev_b32_e32 v155, 5, v155
	v_add_u32_e32 v244, 0, v155
	v_xor_b32_e32 v244, v244, v165
	v_lshl_add_u32 v244, v244, 4, v156
	v_add_u32_e32 v245, 2, v155
	v_xor_b32_e32 v245, v245, v165
	v_lshl_add_u32 v245, v245, 4, v156
	v_add_u32_e32 v246, 4, v155
	v_xor_b32_e32 v246, v246, v165
	v_lshl_add_u32 v246, v246, 4, v156
	v_add_u32_e32 v193, 6, v155
	v_xor_b32_e32 v193, v193, v165
	v_lshl_add_u32 v193, v193, 4, v156
	s_mov_b32 s80, 0x4000
	s_mov_b32 s81, 0
	s_mov_b32 s82, 0xffff4000
	s_mov_b32 s83, -1
	s_and_b32 s76, s2, 0xffffffe0
	s_and_b32 s77, s2, 7
	s_lshl_b32 s77, s77, 2
	s_or_b32 s76, s76, s77
	s_bfe_u32 s77, s2, 0x20003
	s_or_b32 s76, s76, s77
	s_and_b32 s77, s3, 31
	s_cmp_eq_u32 s77, 0
	s_cselect_b32 s76, s76, s2
	v_and_b32_e32 v6, 1, v1
	v_lshlrev_b32_e32 v34, 4, v6
	v_mov_b32_e32 v35, 0
	s_lshr_b32 s0, s0, 6
	s_mov_b32 s5, 0
	v_lshl_add_u64 v[2:3], s[34:35], 0, v[34:35]
	s_lshl_b32 s4, s0, 8
	v_lshl_add_u64 v[36:37], v[2:3], 0, s[4:5]
	v_mbcnt_lo_u32_b32 v2, -1, 0
	v_and_b32_e32 v42, 31, v162
	v_lshl_add_u64 v[4:5], s[52:53], 0, v[34:35]
	v_mbcnt_hi_u32_b32 v2, -1, v2
	v_lshlrev_b32_e32 v6, 10, v6
	v_lshlrev_b32_e32 v7, 2, v42
	v_lshl_add_u64 v[38:39], v[4:5], 0, s[4:5]
	v_and_b32_e32 v4, 64, v2
	v_add3_u32 v7, 0, v6, v7
	v_and_b32_e32 v6, 0x3f00, v164
	v_xor_b32_e32 v3, 8, v2
	v_add_u32_e32 v4, 64, v4
	v_add_u32_e32 v8, 0, v6
	v_and_b32_e32 v6, 8, v162
	s_lshl_b32 s4, s0, 13
	v_cmp_lt_i32_e64 s[0:1], v3, v4
	v_and_b32_e32 v9, 0xf0, v164
	v_cmp_eq_u32_e32 vcc, 0, v6
	v_and_b32_e32 v6, 28, v163
	v_cndmask_b32_e64 v2, v2, v3, s[0:1]
	v_add_u32_e32 v45, s4, v7
	v_lshrrev_b32_e32 v43, 4, v162
	v_lshlrev_b32_e32 v44, 2, v2
	s_lshl_b32 s8, s76, 3
	s_lshl_b32 s9, s3, 3
	s_lshl_b32 s10, s76, 5
	s_lshl_b32 s11, s3, 5
	s_mov_b32 s12, 0x40000
	v_add_u32_e32 v46, v8, v9
	v_mov_b32_e32 v47, 0x358637bd
	s_mov_b32 s13, 0x800000
	v_lshlrev_b32_e32 v40, 1, v6
	v_add_u32_e32 v48, 0x800, v45
	v_add_u32_e32 v49, 0x1000, v45
	v_add_u32_e32 v50, 0x1800, v45
	s_mov_b32 s14, s76
	s_branch .LBB0_619

; #define LAS __attribute__((address_space(3)))
; #define PG8_WAIT_V(n) asm volatile("s_waitcnt vmcnt(" #n ")" ::: "memory")
; #define PG8_BAR __builtin_amdgcn_s_barrier()
; template <class Epi, bool ALIGN_EPI>
; __device__ __forceinline__ void gemm_phase(LAS unsigned char* lds, const Gemm g, const StaticOrder& S, const Epi& E) {
;     ...
;         cur = nxt; cA = nA; cB = nB; ++ui;
;         if constexpr (ALIGN_EPI) { if (wr == 1) PG8_BAR; }
;     }
;     PG8_WAIT_V(0);
;     if constexpr (!ALIGN_EPI) { if (wr == 0) PG8_BAR; }
;     PG8_BAR;
; template <class EpiS>
; DI void sample_gemm(LAS unsigned char* lds, const bf16_t* A, const bf16_t* Bt, int nN, int K, const EpiS& E) {
;     const int tid = threadIdx.x, lane = tid & 63, w = __builtin_amdgcn_readfirstlane(tid >> 6), r32 = lane & 31, h = lane >> 5;
;     const int nunits = 16 * nN, kw = K >> 3, nk = kw >> 4;
;     for (int un = (int)blockIdx.x; un < nunits; un += (int)gridDim.x) {
;         const int rb = un & 3, wc = (un >> 2) & 3, pn = un >> 4;
;         const bf16_t* ap = A + (size_t)(MP + rb * 32 + r32) * K + w * kw + h * 8;
;         const bf16_t* b0p = Bt + (size_t)(pn * 256 + wc * 32 + r32) * K + w * kw + h * 8;
;         const bf16_t* b1p = b0p + (size_t)128 * K;
;         f32x16 c0, c1;
; #pragma unroll
;         for (int r = 0; r < 16; ++r) { c0[r] = 0.f; c1[r] = 0.f; }
; #pragma unroll 8
;         for (int ks = 0; ks < nk; ++ks) {
;             const bf16x8 a = *(const bf16x8*)(ap + ks * 16), b0 = *(const bf16x8*)(b0p + ks * 16), b1 = *(const bf16x8*)(b1p + ks * 16);
;             c0 = __builtin_amdgcn_mfma_f32_32x32x16_bf16(a, b0, c0, 0, 0, 0);
;             c1 = __builtin_amdgcn_mfma_f32_32x32x16_bf16(a, b1, c1, 0, 0, 0);
;         }
;         __syncthreads();
;         LAS float* part = (LAS float*)(lds + w * 8192);
; #pragma unroll
;         for (int r = 0; r < 16; ++r) { const int row = (r & 3) + 8 * (r >> 2) + 4 * h; part[row * 64 + r32] = c0[r]; part[row * 64 + 32 + r32] = c1[r]; }
;         __syncthreads();
;         f32x4 v = (f32x4){0.f, 0.f, 0.f, 0.f};
; #pragma unroll
;         for (int ww = 0; ww < 8; ++ww) v += *(const LAS f32x4*)(lds + ww * 8192 + (tid >> 4) * 256 + (tid & 15) * 16);
.LBB0_715:
	s_or_b64 exec, exec, s[50:51]
	s_and_b64 vcc, exec, s[6:7]
	s_mov_b64 s[6:7], -1
	s_cbranch_vccnz .LBB0_684
	s_andn2_b64 vcc, exec, s[12:13]
	s_cbranch_vccnz .LBB0_683
	s_barrier
	s_branch .LBB0_683
.LBB0_718:
	s_barrier
.LBB0_719:
	s_cmp_gt_i32 s2, 63
	v_readfirstlane_b32 s0, v189
	s_cbranch_scc1 .LBB0_724
	v_and_b32_e32 v155, 63, v189
	v_lshrrev_b32_e32 v156, 6, v189
	v_and_b32_e32 v156, 7, v156
	v_lshlrev_b32_e32 v156, 13, v156
	v_add_u32_e32 v156, 0x10000, v156
	v_lshrrev_b32_e32 v182, 2, v155
	v_and_b32_e32 v165, 31, v155
	v_sub_u32_e32 v182, v182, v165
	v_mul_i32_i24_e32 v182, 0x1600, v182
	v_and_b32_e32 v165, 3, v155
	v_lshrrev_b32_e32 v183, 5, v155
	v_sub_u32_e32 v165, v165, v183
	v_lshl_add_u32 v182, v165, 4, v182
	v_ashrrev_i32_e32 v183, 31, v182
	v_lshrrev_b32_e32 v194, 4, v155
	v_xor_b32_e32 v194, v194, v155
	v_and_b32_e32 v194, 3, v194
	v_lshlrev_b32_e32 v194, 4, v194
	v_lshrrev_b32_e32 v165, 2, v155
	v_lshl_add_u32 v194, v165, 6, v194
	v_add_u32_e32 v194, v156, v194
	v_and_b32_e32 v165, 31, v155
	v_lshl_add_u32 v156, v165, 6, v156
	v_lshrrev_b32_e32 v165, 2, v155
	v_and_b32_e32 v165, 3, v165
	v_lshrrev_b32_e32 v155, 5, v155
	v_add_u32_e32 v244, 0, v155
	v_xor_b32_e32 v244, v244, v165
	v_lshl_add_u32 v244, v244, 4, v156
	v_add_u32_e32 v245, 2, v155
	v_xor_b32_e32 v245, v245, v165
	v_lshl_add_u32 v245, v245, 4, v156
	s_mov_b32 s80, 0x16000
	s_mov_b32 s81, 0
	s_and_b32 s76, s2, 0xffffffe0
	s_and_b32 s77, s2, 7
	s_lshl_b32 s77, s77, 2
	s_or_b32 s76, s76, s77
	s_bfe_u32 s77, s2, 0x20003
	s_or_b32 s76, s76, s77
	s_and_b32 s77, s3, 31
	s_cmp_eq_u32 s77, 0
	s_cselect_b32 s76, s76, s2
	s_lshr_b32 s6, s0, 6
	s_mul_i32 s0, s6, 0x160
	s_mov_b32 s1, 0
	s_lshl_b64 s[0:1], s[0:1], 1
	s_add_u32 s4, s24, s0
	s_addc_u32 s5, s25, s1
	v_bfe_u32 v2, v189, 5, 1
	s_add_u32 s0, s33, s0
	v_lshlrev_b32_e32 v34, 4, v2
	v_mov_b32_e32 v35, 0
	s_addc_u32 s1, s56, s1
	v_and_b32_e32 v40, 31, v189
	v_lshl_add_u64 v[38:39], s[0:1], 0, v[34:35]
	s_lshl_b32 s0, s6, 13
	s_add_i32 s0, s0, 0
	v_lshlrev_b32_e32 v2, 10, v2
	s_waitcnt lgkmcnt(0)
	v_lshlrev_b32_e32 v3, 2, v40
	v_add3_u32 v41, s0, v2, v3
	v_and_b32_e32 v4, 28, v192
	s_movk_i32 s0, 0x80
	v_and_or_b32 v42, v191, s0, v4
	v_mbcnt_lo_u32_b32 v4, -1, 0
	v_mbcnt_hi_u32_b32 v4, -1, v4
	v_and_b32_e32 v6, 64, v4
	v_xor_b32_e32 v5, 1, v4
	v_add_u32_e32 v6, 64, v6
	v_cmp_lt_i32_e32 vcc, v5, v6
	v_and_b32_e32 v2, 0x3f00, v191
	v_add_u32_e32 v2, 0, v2
	v_cndmask_b32_e32 v5, v4, v5, vcc
	v_lshlrev_b32_e32 v43, 2, v5
	v_xor_b32_e32 v5, 2, v4
	v_cmp_lt_i32_e32 vcc, v5, v6
	v_and_b32_e32 v3, 0xf0, v191
	v_lshl_add_u64 v[36:37], s[4:5], 0, v[34:35]
	v_cndmask_b32_e32 v5, v4, v5, vcc
	v_lshlrev_b32_e32 v44, 2, v5
	v_xor_b32_e32 v5, 4, v4
	v_cmp_lt_i32_e32 vcc, v5, v6
	s_lshl_b32 s4, s76, 3
	s_lshl_b32 s5, s3, 3
	v_cndmask_b32_e32 v5, v4, v5, vcc
	v_lshlrev_b32_e32 v45, 2, v5
	v_xor_b32_e32 v5, 8, v4
	v_cmp_lt_i32_e32 vcc, v5, v6
	s_lshl_b32 s6, s76, 4
	s_lshl_b32 s7, s3, 4
	v_cndmask_b32_e32 v4, v4, v5, vcc
	v_lshlrev_b32_e32 v46, 2, v4
	v_cmp_eq_u32_e32 vcc, 0, v190
	s_lshl_b32 s12, s76, 5
	s_lshl_b32 s13, s3, 5
	s_movk_i32 s14, 0x1600
	s_mov_b32 s15, 0xb0000
	v_add_u32_e32 v47, v2, v3
	v_add_u32_e32 v48, 0x800, v41
	v_add_u32_e32 v49, 0x1000, v41
	v_add_u32_e32 v50, 0x1800, v41
	s_mov_b32 s16, s76
	s_branch .LBB0_722

; #define PG8_WAIT_V(n) asm volatile("s_waitcnt vmcnt(" #n ")" ::: "memory")
; #define PG8_BAR __builtin_amdgcn_s_barrier()
; template <class Epi, bool ALIGN_EPI>
; __device__ __forceinline__ void gemm_phase(LAS unsigned char* lds, const Gemm g, const StaticOrder& S, const Epi& E) {
;     ...
;     PG8_WAIT_V(0);
;     if constexpr (!ALIGN_EPI) { if (wr == 0) PG8_BAR; }
;     PG8_BAR;
.LBB0_931:
	v_readlane_b32 s52, v247, 5
	v_readlane_b32 s53, v247, 6
	s_barrier

; #define LAS __attribute__((address_space(3)))
; #define PG8_WAIT_V(n) asm volatile("s_waitcnt vmcnt(" #n ")" ::: "memory")
; #define PG8_BAR __builtin_amdgcn_s_barrier()
; template <class Epi, bool ALIGN_EPI>
; __device__ __forceinline__ void gemm_phase(LAS unsigned char* lds, const Gemm g, const StaticOrder& S, const Epi& E) {
;     ...
;         cur = nxt; cA = nA; cB = nB; ++ui;
;         if constexpr (ALIGN_EPI) { if (wr == 1) PG8_BAR; }
;     }
;     PG8_WAIT_V(0);
;     if constexpr (!ALIGN_EPI) { if (wr == 0) PG8_BAR; }
;     PG8_BAR;
; template <class EpiS>
; DI void sample_gemm(LAS unsigned char* lds, const bf16_t* A, const bf16_t* Bt, int nN, int K, const EpiS& E) {
;     const int tid = threadIdx.x, lane = tid & 63, w = __builtin_amdgcn_readfirstlane(tid >> 6), r32 = lane & 31, h = lane >> 5;
;     const int nunits = 16 * nN, kw = K >> 3, nk = kw >> 4;
;     for (int un = (int)blockIdx.x; un < nunits; un += (int)gridDim.x) {
;         const int rb = un & 3, wc = (un >> 2) & 3, pn = un >> 4;
;         const bf16_t* ap = A + (size_t)(MP + rb * 32 + r32) * K + w * kw + h * 8;
;         const bf16_t* b0p = Bt + (size_t)(pn * 256 + wc * 32 + r32) * K + w * kw + h * 8;
;         const bf16_t* b1p = b0p + (size_t)128 * K;
;         f32x16 c0, c1;
; #pragma unroll
;         for (int r = 0; r < 16; ++r) { c0[r] = 0.f; c1[r] = 0.f; }
; #pragma unroll 8
;         for (int ks = 0; ks < nk; ++ks) {
;             const bf16x8 a = *(const bf16x8*)(ap + ks * 16), b0 = *(const bf16x8*)(b0p + ks * 16), b1 = *(const bf16x8*)(b1p + ks * 16);
;             c0 = __builtin_amdgcn_mfma_f32_32x32x16_bf16(a, b0, c0, 0, 0, 0);
;             c1 = __builtin_amdgcn_mfma_f32_32x32x16_bf16(a, b1, c1, 0, 0, 0);
;         }
;         __syncthreads();
;         LAS float* part = (LAS float*)(lds + w * 8192);
; #pragma unroll
;         for (int r = 0; r < 16; ++r) { const int row = (r & 3) + 8 * (r >> 2) + 4 * h; part[row * 64 + r32] = c0[r]; part[row * 64 + 32 + r32] = c1[r]; }
;         __syncthreads();
;         f32x4 v = (f32x4){0.f, 0.f, 0.f, 0.f};
; #pragma unroll
;         for (int ww = 0; ww < 8; ++ww) v += *(const LAS f32x4*)(lds + ww * 8192 + (tid >> 4) * 256 + (tid & 15) * 16);
.LBB0_1358:
	s_or_b64 exec, exec, s[36:37]
	s_andn2_b64 vcc, exec, s[4:5]
	s_mov_b64 s[4:5], -1
	s_cbranch_vccnz .LBB0_1331
	s_andn2_b64 vcc, exec, s[10:11]
	s_cbranch_vccnz .LBB0_1330
	s_barrier
	s_branch .LBB0_1330
.LBB0_1361:
	s_barrier
.LBB0_1362:
	s_cmp_gt_i32 s2, 63
	v_readfirstlane_b32 s0, v189
	s_cbranch_scc1 .LBB0_1367
	v_and_b32_e32 v155, 63, v189
	v_lshrrev_b32_e32 v156, 6, v189
	v_and_b32_e32 v156, 7, v156
	v_lshlrev_b32_e32 v156, 13, v156
	v_add_u32_e32 v156, 0x10000, v156
	v_lshrrev_b32_e32 v182, 3, v155
	v_and_b32_e32 v165, 31, v155
	v_sub_u32_e32 v182, v182, v165
	v_lshlrev_b32_e32 v182, 11, v182
	v_and_b32_e32 v165, 7, v155
	v_lshrrev_b32_e32 v183, 5, v155
	v_sub_u32_e32 v165, v165, v183
	v_lshl_add_u32 v182, v165, 4, v182
	v_ashrrev_i32_e32 v183, 31, v182
	v_lshrrev_b32_e32 v194, 4, v155
	v_and_b32_e32 v194, 3, v194
	v_and_b32_e32 v165, 7, v155
	v_xor_b32_e32 v194, v194, v165
	v_lshlrev_b32_e32 v194, 4, v194
	v_lshrrev_b32_e32 v165, 3, v155
	v_lshl_add_u32 v194, v165, 7, v194
	v_add_u32_e32 v194, v156, v194
	v_xor_b32_e32 v195, 64, v194
	v_and_b32_e32 v165, 31, v155
	v_lshl_add_u32 v156, v165, 7, v156
	v_lshrrev_b32_e32 v165, 1, v155
	v_and_b32_e32 v165, 7, v165
	v_lshrrev_b32_e32 v155, 5, v155
	v_add_u32_e32 v244, 0, v155
	v_xor_b32_e32 v244, v244, v165
	v_lshl_add_u32 v244, v244, 4, v156
	v_add_u32_e32 v245, 2, v155
	v_xor_b32_e32 v245, v245, v165
	v_lshl_add_u32 v245, v245, 4, v156
	v_add_u32_e32 v246, 4, v155
	v_xor_b32_e32 v246, v246, v165
	v_lshl_add_u32 v246, v246, 4, v156
	v_add_u32_e32 v193, 6, v155
	v_xor_b32_e32 v193, v193, v165
	v_lshl_add_u32 v193, v193, 4, v156
	s_mov_b32 s80, 0x4000
	s_mov_b32 s81, 0
	s_mov_b32 s82, 0xffff4000
	s_mov_b32 s83, -1
	s_and_b32 s76, s2, 0xffffffe0
	s_and_b32 s77, s2, 7
	s_lshl_b32 s77, s77, 2
	s_or_b32 s76, s76, s77
	s_bfe_u32 s77, s2, 0x20003
	s_or_b32 s76, s76, s77
	s_and_b32 s77, s3, 31
	s_cmp_eq_u32 s77, 0
	s_cselect_b32 s76, s76, s2
	s_lshr_b32 s4, s0, 6
	s_lshl_b32 s5, s4, 8
	v_bfe_u32 v2, v189, 5, 1
	s_add_u32 s0, s26, s5
	s_addc_u32 s1, s27, 0
	v_lshlrev_b32_e32 v34, 4, v2
	v_mov_b32_e32 v35, 0
	v_lshl_add_u64 v[36:37], s[0:1], 0, v[34:35]
	s_add_u32 s0, s33, s5
	s_addc_u32 s1, s46, 0
	v_and_b32_e32 v40, 31, v189
	v_lshl_add_u64 v[38:39], s[0:1], 0, v[34:35]
	s_lshl_b32 s0, s4, 13
	s_add_i32 s0, s0, 0
	v_lshlrev_b32_e32 v2, 10, v2
	s_waitcnt lgkmcnt(0)
	v_lshlrev_b32_e32 v3, 2, v40
	v_add3_u32 v41, s0, v2, v3
	v_and_b32_e32 v4, 28, v192
	s_movk_i32 s0, 0x80
	v_and_or_b32 v42, v191, s0, v4
	v_mbcnt_lo_u32_b32 v4, -1, 0
	v_mbcnt_hi_u32_b32 v4, -1, v4
	v_and_b32_e32 v6, 64, v4
	v_xor_b32_e32 v5, 1, v4
	v_add_u32_e32 v6, 64, v6
	v_cmp_lt_i32_e32 vcc, v5, v6
	v_and_b32_e32 v2, 0x3f00, v191
	v_add_u32_e32 v2, 0, v2
	v_cndmask_b32_e32 v5, v4, v5, vcc
	v_lshlrev_b32_e32 v43, 2, v5
	v_xor_b32_e32 v5, 2, v4
	v_cmp_lt_i32_e32 vcc, v5, v6
	v_and_b32_e32 v3, 0xf0, v191
	s_lshl_b32 s4, s76, 3
	v_cndmask_b32_e32 v5, v4, v5, vcc
	v_lshlrev_b32_e32 v44, 2, v5
	v_xor_b32_e32 v5, 4, v4
	v_cmp_lt_i32_e32 vcc, v5, v6
	s_lshl_b32 s5, s3, 3
	s_lshl_b32 s10, s76, 4
	v_cndmask_b32_e32 v5, v4, v5, vcc
	v_lshlrev_b32_e32 v45, 2, v5
	v_xor_b32_e32 v5, 8, v4
	v_cmp_lt_i32_e32 vcc, v5, v6
	s_lshl_b32 s11, s3, 4
	s_lshl_b32 s12, s76, 5
	v_cndmask_b32_e32 v4, v4, v5, vcc
	v_lshlrev_b32_e32 v46, 2, v4
	v_cmp_eq_u32_e32 vcc, 0, v190
	s_lshl_b32 s13, s3, 5
	s_mov_b32 s14, 0x40000
	v_add_u32_e32 v47, v2, v3
	v_add_u32_e32 v48, 0x800, v41
	v_add_u32_e32 v49, 0x1000, v41
	v_add_u32_e32 v50, 0x1800, v41
	s_mov_b32 s15, s76
	s_branch .LBB0_1365

; DI u32x4 pk8(f32x4 a, f32x4 b) { u32x4 w; w.x = pk2(a[0], a[1]); w.y = pk2(a[2], a[3]); w.z = pk2(b[0], b[1]); w.w = pk2(b[2], b[3]); return w; }
; DI float row_rstd(const float* SS, int row) { return rsqrtf(SS[row] * (1.0f / 1024.0f) + 1e-6f); }
;     DI void operator()(const Acc& acc, const pg8::Unit& u, int wr, int wc, int fr, int fq) const {
;         const int colb = u.pn * 128 + wc * 32 + fq * 8;
;         float rsv[2][4];
; #pragma unroll
;         for (int ai = 0; ai < 2; ++ai)
; #pragma unroll
;             for (int m = 0; m < 4; ++m) rsv[ai][m] = row_rstd(SS, u.pm * 256 + ai * 128 + wr * 64 + m * 16 + fr);
; #pragma unroll
;         for (int ai = 0; ai < 2; ++ai)
; #pragma unroll
;             for (int m = 0; m < 4; ++m) {
;                 const int row = u.pm * 256 + ai * 128 + wr * 64 + m * 16 + fr;
;                 const float rs = rsv[ai][m];
;                 f32x4 h0, h1;
;                 const float rs2 = rs * rs, nrl = -rs * LOG2E;
; #pragma unroll
;                 for (int i = 0; i < 4; ++i) {
;                     const float a0 = acc[ai][0][m][0][i], a1 = acc[ai][0][m][1][i];
;                     h0[i] = (a0 * acc[ai][1][m][0][i]) * rs2 * __builtin_amdgcn_rcpf(1.0f + __builtin_amdgcn_exp2f(a0 * nrl));
;                     h1[i] = (a1 * acc[ai][1][m][1][i]) * rs2 * __builtin_amdgcn_rcpf(1.0f + __builtin_amdgcn_exp2f(a1 * nrl));
;                 }
;                 __builtin_nontemporal_store(pk8(h0, h1), (u32x4*)(HID + (size_t)row * FH + colb));
;             }
.LBB0_1431:
	v_lshl_add_u32 v160, s4, 8, v165
	v_lshlrev_b32_e32 v185, 2, v160
	global_load_dword v146, v185, s[20:21]
	global_load_dword v147, v185, s[20:21] offset:64
	global_load_dword v148, v185, s[20:21] offset:128
	global_load_dword v149, v185, s[20:21] offset:192
	global_load_dword v150, v185, s[20:21] offset:512
	global_load_dword v151, v185, s[20:21] offset:576
	global_load_dword v152, v185, s[20:21] offset:640
	global_load_dword v153, v185, s[20:21] offset:704
	v_lshl_or_b32 v181, s5, 7, v167
	v_lshlrev_b32_e32 v181, 1, v181
	v_mad_u32_u24 v183, v160, s61, v181
	v_pk_mul_f32 v[122:123], v[126:127], v[122:123]
	v_pk_mul_f32 v[124:125], v[128:129], v[124:125]
	v_pk_mul_f32 v[114:115], v[118:119], v[114:115]
	v_pk_mul_f32 v[116:117], v[120:121], v[116:117]
	v_pk_mul_f32 v[106:107], v[110:111], v[106:107]
	v_pk_mul_f32 v[108:109], v[112:113], v[108:109]
	v_pk_mul_f32 v[98:99], v[102:103], v[98:99]
	v_pk_mul_f32 v[100:101], v[104:105], v[100:101]
	v_pk_mul_f32 v[90:91], v[94:95], v[90:91]
	v_pk_mul_f32 v[92:93], v[96:97], v[92:93]
	v_pk_mul_f32 v[82:83], v[86:87], v[82:83]
	v_pk_mul_f32 v[84:85], v[88:89], v[84:85]
	v_pk_mul_f32 v[74:75], v[78:79], v[74:75]
	v_pk_mul_f32 v[76:77], v[80:81], v[76:77]
	v_pk_mul_f32 v[66:67], v[70:71], v[66:67]
	v_pk_mul_f32 v[68:69], v[72:73], v[68:69]
	v_pk_mul_f32 v[58:59], v[62:63], v[58:59]
	v_pk_mul_f32 v[60:61], v[64:65], v[60:61]
	v_pk_mul_f32 v[50:51], v[54:55], v[50:51]
	v_pk_mul_f32 v[52:53], v[56:57], v[52:53]
	v_pk_mul_f32 v[42:43], v[46:47], v[42:43]
	v_pk_mul_f32 v[44:45], v[48:49], v[44:45]
	v_pk_mul_f32 v[34:35], v[38:39], v[34:35]
	v_pk_mul_f32 v[36:37], v[40:41], v[36:37]
	v_pk_mul_f32 v[26:27], v[30:31], v[26:27]
	v_pk_mul_f32 v[28:29], v[32:33], v[28:29]
	v_pk_mul_f32 v[18:19], v[22:23], v[18:19]
	v_pk_mul_f32 v[20:21], v[24:25], v[20:21]
	v_pk_mul_f32 v[10:11], v[14:15], v[10:11]
	v_pk_mul_f32 v[12:13], v[16:17], v[12:13]
	v_pk_mul_f32 v[2:3], v[6:7], v[2:3]
	v_pk_mul_f32 v[4:5], v[8:9], v[4:5]
	s_andn2_b64 vcc, exec, s[0:1]
	s_mov_b64 s[0:1], -1
	s_waitcnt vmcnt(0)
	v_fmamk_f32 v232, v146, 0x3a800000, v171
	v_fmamk_f32 v234, v147, 0x3a800000, v171
	v_fmamk_f32 v236, v148, 0x3a800000, v171
	v_fmamk_f32 v238, v149, 0x3a800000, v171
	v_fmamk_f32 v240, v150, 0x3a800000, v171
	v_fmamk_f32 v242, v151, 0x3a800000, v171
	v_fmamk_f32 v244, v152, 0x3a800000, v171
	v_fmamk_f32 v246, v153, 0x3a800000, v171
	v_rsq_f32_e32 v154, v232
	v_rsq_f32_e32 v155, v234
	v_rsq_f32_e32 v156, v236
	v_rsq_f32_e32 v157, v238
	v_rsq_f32_e32 v158, v240
	v_rsq_f32_e32 v159, v242
	v_rsq_f32_e32 v160, v244
	v_rsq_f32_e32 v161, v246
	v_mul_f32_e32 v172, 0xbfb8aa3b, v154
	v_mul_f32_e32 v174, 0xbfb8aa3b, v155
	v_mul_f32_e32 v176, 0xbfb8aa3b, v156
	v_mul_f32_e32 v178, 0xbfb8aa3b, v157
	v_mul_f32_e32 v180, 0xbfb8aa3b, v158
	v_mul_f32_e32 v182, 0xbfb8aa3b, v159
	v_mul_f32_e32 v184, 0xbfb8aa3b, v160
	v_mul_f32_e32 v230, 0xbfb8aa3b, v161
	v_pk_mul_f32 v[126:127], v[126:127], v[172:173] op_sel_hi:[1,0]
	v_pk_mul_f32 v[128:129], v[128:129], v[172:173] op_sel_hi:[1,0]
	v_pk_mul_f32 v[118:119], v[118:119], v[172:173] op_sel_hi:[1,0]
	v_pk_mul_f32 v[120:121], v[120:121], v[172:173] op_sel_hi:[1,0]
	v_exp_f32_e32 v126, v126
	v_exp_f32_e32 v127, v127
	v_exp_f32_e32 v128, v128
	v_exp_f32_e32 v129, v129
	v_exp_f32_e32 v118, v118
	v_exp_f32_e32 v119, v119
	v_exp_f32_e32 v120, v120
	v_exp_f32_e32 v121, v121
	v_pk_fma_f32 v[126:127], v[126:127], v[232:233], v[232:233] op_sel_hi:[1,0,0]
	v_pk_fma_f32 v[128:129], v[128:129], v[232:233], v[232:233] op_sel_hi:[1,0,0]
	v_pk_fma_f32 v[118:119], v[118:119], v[232:233], v[232:233] op_sel_hi:[1,0,0]
	v_pk_fma_f32 v[120:121], v[120:121], v[232:233], v[232:233] op_sel_hi:[1,0,0]
	v_rcp_f32_e32 v126, v126
	v_rcp_f32_e32 v127, v127
	v_rcp_f32_e32 v128, v128
	v_rcp_f32_e32 v129, v129
	v_rcp_f32_e32 v118, v118
	v_rcp_f32_e32 v119, v119
	v_rcp_f32_e32 v120, v120
	v_rcp_f32_e32 v121, v121
	v_pk_mul_f32 v[122:123], v[122:123], v[126:127]
	v_pk_mul_f32 v[124:125], v[124:125], v[128:129]
	v_pk_mul_f32 v[114:115], v[114:115], v[118:119]
	v_pk_mul_f32 v[116:117], v[116:117], v[120:121]
	v_cvt_pk_bf16_f32 v122, v122, v123
	v_cvt_pk_bf16_f32 v123, v124, v125
	v_cvt_pk_bf16_f32 v124, v114, v115
	v_cvt_pk_bf16_f32 v125, v116, v117
	global_store_dwordx4 v183, v[122:125], s[24:25] nt
	v_add_u32_e32 v183, 0x16000, v183
	v_pk_mul_f32 v[110:111], v[110:111], v[174:175] op_sel_hi:[1,0]
	v_pk_mul_f32 v[112:113], v[112:113], v[174:175] op_sel_hi:[1,0]
	v_pk_mul_f32 v[102:103], v[102:103], v[174:175] op_sel_hi:[1,0]
	v_pk_mul_f32 v[104:105], v[104:105], v[174:175] op_sel_hi:[1,0]
	v_exp_f32_e32 v110, v110
	v_exp_f32_e32 v111, v111
	v_exp_f32_e32 v112, v112
	v_exp_f32_e32 v113, v113
	v_exp_f32_e32 v102, v102
	v_exp_f32_e32 v103, v103
	v_exp_f32_e32 v104, v104
	v_exp_f32_e32 v105, v105
	v_pk_fma_f32 v[110:111], v[110:111], v[234:235], v[234:235] op_sel_hi:[1,0,0]
	v_pk_fma_f32 v[112:113], v[112:113], v[234:235], v[234:235] op_sel_hi:[1,0,0]
	v_pk_fma_f32 v[102:103], v[102:103], v[234:235], v[234:235] op_sel_hi:[1,0,0]
	v_pk_fma_f32 v[104:105], v[104:105], v[234:235], v[234:235] op_sel_hi:[1,0,0]
	v_rcp_f32_e32 v110, v110
	v_rcp_f32_e32 v111, v111
	v_rcp_f32_e32 v112, v112
	v_rcp_f32_e32 v113, v113
	v_rcp_f32_e32 v102, v102
	v_rcp_f32_e32 v103, v103
	v_rcp_f32_e32 v104, v104
	v_rcp_f32_e32 v105, v105
	v_pk_mul_f32 v[106:107], v[106:107], v[110:111]
	v_pk_mul_f32 v[108:109], v[108:109], v[112:113]
	v_pk_mul_f32 v[98:99], v[98:99], v[102:103]
	v_pk_mul_f32 v[100:101], v[100:101], v[104:105]
	v_cvt_pk_bf16_f32 v106, v106, v107
	v_cvt_pk_bf16_f32 v107, v108, v109
	v_cvt_pk_bf16_f32 v108, v98, v99
	v_cvt_pk_bf16_f32 v109, v100, v101
; DI u32x4 pk8(f32x4 a, f32x4 b) { u32x4 w; w.x = pk2(a[0], a[1]); w.y = pk2(a[2], a[3]); w.z = pk2(b[0], b[1]); w.w = pk2(b[2], b[3]); return w; }
;     DI void operator()(const Acc& acc, const pg8::Unit& u, int wr, int wc, int fr, int fq) const {
;     ...
; #pragma unroll
;                 for (int i = 0; i < 4; ++i) {
;                     const float a0 = acc[ai][0][m][0][i], a1 = acc[ai][0][m][1][i];
;                     h0[i] = (a0 * acc[ai][1][m][0][i]) * rs2 * __builtin_amdgcn_rcpf(1.0f + __builtin_amdgcn_exp2f(a0 * nrl));
;                     h1[i] = (a1 * acc[ai][1][m][1][i]) * rs2 * __builtin_amdgcn_rcpf(1.0f + __builtin_amdgcn_exp2f(a1 * nrl));
;                 }
;                 __builtin_nontemporal_store(pk8(h0, h1), (u32x4*)(HID + (size_t)row * FH + colb));
	global_store_dwordx4 v183, v[106:109], s[24:25] nt
	v_add_u32_e32 v183, 0x16000, v183
	v_pk_mul_f32 v[94:95], v[94:95], v[176:177] op_sel_hi:[1,0]
	v_pk_mul_f32 v[96:97], v[96:97], v[176:177] op_sel_hi:[1,0]
	v_pk_mul_f32 v[86:87], v[86:87], v[176:177] op_sel_hi:[1,0]
	v_pk_mul_f32 v[88:89], v[88:89], v[176:177] op_sel_hi:[1,0]
	v_exp_f32_e32 v94, v94
	v_exp_f32_e32 v95, v95
	v_exp_f32_e32 v96, v96
	v_exp_f32_e32 v97, v97
	v_exp_f32_e32 v86, v86
	v_exp_f32_e32 v87, v87
	v_exp_f32_e32 v88, v88
	v_exp_f32_e32 v89, v89
	v_pk_fma_f32 v[94:95], v[94:95], v[236:237], v[236:237] op_sel_hi:[1,0,0]
	v_pk_fma_f32 v[96:97], v[96:97], v[236:237], v[236:237] op_sel_hi:[1,0,0]
	v_pk_fma_f32 v[86:87], v[86:87], v[236:237], v[236:237] op_sel_hi:[1,0,0]
	v_pk_fma_f32 v[88:89], v[88:89], v[236:237], v[236:237] op_sel_hi:[1,0,0]
	v_rcp_f32_e32 v94, v94
	v_rcp_f32_e32 v95, v95
	v_rcp_f32_e32 v96, v96
	v_rcp_f32_e32 v97, v97
	v_rcp_f32_e32 v86, v86
	v_rcp_f32_e32 v87, v87
	v_rcp_f32_e32 v88, v88
	v_rcp_f32_e32 v89, v89
	v_pk_mul_f32 v[90:91], v[90:91], v[94:95]
	v_pk_mul_f32 v[92:93], v[92:93], v[96:97]
	v_pk_mul_f32 v[82:83], v[82:83], v[86:87]
	v_pk_mul_f32 v[84:85], v[84:85], v[88:89]
	v_cvt_pk_bf16_f32 v90, v90, v91
	v_cvt_pk_bf16_f32 v91, v92, v93
	v_cvt_pk_bf16_f32 v92, v82, v83
	v_cvt_pk_bf16_f32 v93, v84, v85
	global_store_dwordx4 v183, v[90:93], s[24:25] nt
	v_add_u32_e32 v183, 0x16000, v183
	v_pk_mul_f32 v[78:79], v[78:79], v[178:179] op_sel_hi:[1,0]
	v_pk_mul_f32 v[80:81], v[80:81], v[178:179] op_sel_hi:[1,0]
	v_pk_mul_f32 v[70:71], v[70:71], v[178:179] op_sel_hi:[1,0]
	v_pk_mul_f32 v[72:73], v[72:73], v[178:179] op_sel_hi:[1,0]
	v_exp_f32_e32 v78, v78
	v_exp_f32_e32 v79, v79
	v_exp_f32_e32 v80, v80
	v_exp_f32_e32 v81, v81
	v_exp_f32_e32 v70, v70
	v_exp_f32_e32 v71, v71
	v_exp_f32_e32 v72, v72
	v_exp_f32_e32 v73, v73
	v_pk_fma_f32 v[78:79], v[78:79], v[238:239], v[238:239] op_sel_hi:[1,0,0]
	v_pk_fma_f32 v[80:81], v[80:81], v[238:239], v[238:239] op_sel_hi:[1,0,0]
	v_pk_fma_f32 v[70:71], v[70:71], v[238:239], v[238:239] op_sel_hi:[1,0,0]
	v_pk_fma_f32 v[72:73], v[72:73], v[238:239], v[238:239] op_sel_hi:[1,0,0]
	v_rcp_f32_e32 v78, v78
	v_rcp_f32_e32 v79, v79
	v_rcp_f32_e32 v80, v80
	v_rcp_f32_e32 v81, v81
	v_rcp_f32_e32 v70, v70
	v_rcp_f32_e32 v71, v71
	v_rcp_f32_e32 v72, v72
	v_rcp_f32_e32 v73, v73
	v_pk_mul_f32 v[74:75], v[74:75], v[78:79]
	v_pk_mul_f32 v[76:77], v[76:77], v[80:81]
	v_pk_mul_f32 v[66:67], v[66:67], v[70:71]
	v_pk_mul_f32 v[68:69], v[68:69], v[72:73]
	v_cvt_pk_bf16_f32 v74, v74, v75
	v_cvt_pk_bf16_f32 v75, v76, v77
	v_cvt_pk_bf16_f32 v76, v66, v67
	v_cvt_pk_bf16_f32 v77, v68, v69
	global_store_dwordx4 v183, v[74:77], s[24:25] nt
	v_add_u32_e32 v183, 0x6e000, v183
	v_pk_mul_f32 v[62:63], v[62:63], v[180:181] op_sel_hi:[1,0]
	v_pk_mul_f32 v[64:65], v[64:65], v[180:181] op_sel_hi:[1,0]
	v_pk_mul_f32 v[54:55], v[54:55], v[180:181] op_sel_hi:[1,0]
	v_pk_mul_f32 v[56:57], v[56:57], v[180:181] op_sel_hi:[1,0]
	v_exp_f32_e32 v62, v62
	v_exp_f32_e32 v63, v63
	v_exp_f32_e32 v64, v64
	v_exp_f32_e32 v65, v65
	v_exp_f32_e32 v54, v54
	v_exp_f32_e32 v55, v55
	v_exp_f32_e32 v56, v56
	v_exp_f32_e32 v57, v57
	v_pk_fma_f32 v[62:63], v[62:63], v[240:241], v[240:241] op_sel_hi:[1,0,0]
	v_pk_fma_f32 v[64:65], v[64:65], v[240:241], v[240:241] op_sel_hi:[1,0,0]
	v_pk_fma_f32 v[54:55], v[54:55], v[240:241], v[240:241] op_sel_hi:[1,0,0]
	v_pk_fma_f32 v[56:57], v[56:57], v[240:241], v[240:241] op_sel_hi:[1,0,0]
	v_rcp_f32_e32 v62, v62
	v_rcp_f32_e32 v63, v63
	v_rcp_f32_e32 v64, v64
	v_rcp_f32_e32 v65, v65
	v_rcp_f32_e32 v54, v54
	v_rcp_f32_e32 v55, v55
	v_rcp_f32_e32 v56, v56
	v_rcp_f32_e32 v57, v57
	v_pk_mul_f32 v[58:59], v[58:59], v[62:63]
	v_pk_mul_f32 v[60:61], v[60:61], v[64:65]
	v_pk_mul_f32 v[50:51], v[50:51], v[54:55]
	v_pk_mul_f32 v[52:53], v[52:53], v[56:57]
	v_cvt_pk_bf16_f32 v58, v58, v59
	v_cvt_pk_bf16_f32 v59, v60, v61
	v_cvt_pk_bf16_f32 v60, v50, v51
	v_cvt_pk_bf16_f32 v61, v52, v53
	global_store_dwordx4 v183, v[58:61], s[24:25] nt
	v_add_u32_e32 v183, 0x16000, v183
	v_pk_mul_f32 v[46:47], v[46:47], v[182:183] op_sel_hi:[1,0]
	v_pk_mul_f32 v[48:49], v[48:49], v[182:183] op_sel_hi:[1,0]
	v_pk_mul_f32 v[38:39], v[38:39], v[182:183] op_sel_hi:[1,0]
	v_pk_mul_f32 v[40:41], v[40:41], v[182:183] op_sel_hi:[1,0]
	v_exp_f32_e32 v46, v46
	v_exp_f32_e32 v47, v47
	v_exp_f32_e32 v48, v48
	v_exp_f32_e32 v49, v49
	v_exp_f32_e32 v38, v38
	v_exp_f32_e32 v39, v39
	v_exp_f32_e32 v40, v40
	v_exp_f32_e32 v41, v41
	v_pk_fma_f32 v[46:47], v[46:47], v[242:243], v[242:243] op_sel_hi:[1,0,0]
	v_pk_fma_f32 v[48:49], v[48:49], v[242:243], v[242:243] op_sel_hi:[1,0,0]
	v_pk_fma_f32 v[38:39], v[38:39], v[242:243], v[242:243] op_sel_hi:[1,0,0]
	v_pk_fma_f32 v[40:41], v[40:41], v[242:243], v[242:243] op_sel_hi:[1,0,0]
	v_rcp_f32_e32 v46, v46
	v_rcp_f32_e32 v47, v47
	v_rcp_f32_e32 v48, v48
	v_rcp_f32_e32 v49, v49
	v_rcp_f32_e32 v38, v38
	v_rcp_f32_e32 v39, v39
	v_rcp_f32_e32 v40, v40
	v_rcp_f32_e32 v41, v41
	v_pk_mul_f32 v[42:43], v[42:43], v[46:47]
	v_pk_mul_f32 v[44:45], v[44:45], v[48:49]
	v_pk_mul_f32 v[34:35], v[34:35], v[38:39]
	v_pk_mul_f32 v[36:37], v[36:37], v[40:41]
	v_cvt_pk_bf16_f32 v42, v42, v43
	v_cvt_pk_bf16_f32 v43, v44, v45
	v_cvt_pk_bf16_f32 v44, v34, v35
	v_cvt_pk_bf16_f32 v45, v36, v37
	global_store_dwordx4 v183, v[42:45], s[24:25] nt
	v_add_u32_e32 v183, 0x16000, v183
	v_pk_mul_f32 v[30:31], v[30:31], v[184:185] op_sel_hi:[1,0]
	v_pk_mul_f32 v[32:33], v[32:33], v[184:185] op_sel_hi:[1,0]
	v_pk_mul_f32 v[22:23], v[22:23], v[184:185] op_sel_hi:[1,0]
; #define LAS __attribute__((address_space(3)))
; DI u32x4 pk8(f32x4 a, f32x4 b) { u32x4 w; w.x = pk2(a[0], a[1]); w.y = pk2(a[2], a[3]); w.z = pk2(b[0], b[1]); w.w = pk2(b[2], b[3]); return w; }
; #define PG8_WAIT_V(n) asm volatile("s_waitcnt vmcnt(" #n ")" ::: "memory")
; #define PG8_BAR __builtin_amdgcn_s_barrier()
; template <class Epi, bool ALIGN_EPI>
; __device__ __forceinline__ void gemm_phase(LAS unsigned char* lds, const Gemm g, const StaticOrder& S, const Epi& E) {
;     ...
;     PG8_WAIT_V(0);
;     if constexpr (!ALIGN_EPI) { if (wr == 0) PG8_BAR; }
;     PG8_BAR;
;     DI void operator()(const Acc& acc, const pg8::Unit& u, int wr, int wc, int fr, int fq) const {
;     ...
; #pragma unroll
;                 for (int i = 0; i < 4; ++i) {
;                     const float a0 = acc[ai][0][m][0][i], a1 = acc[ai][0][m][1][i];
;                     h0[i] = (a0 * acc[ai][1][m][0][i]) * rs2 * __builtin_amdgcn_rcpf(1.0f + __builtin_amdgcn_exp2f(a0 * nrl));
;                     h1[i] = (a1 * acc[ai][1][m][1][i]) * rs2 * __builtin_amdgcn_rcpf(1.0f + __builtin_amdgcn_exp2f(a1 * nrl));
;                 }
;                 __builtin_nontemporal_store(pk8(h0, h1), (u32x4*)(HID + (size_t)row * FH + colb));
; template <class EpiS>
; DI void sample_gemm(LAS unsigned char* lds, const bf16_t* A, const bf16_t* Bt, int nN, int K, const EpiS& E) {
;     const int tid = threadIdx.x, lane = tid & 63, w = __builtin_amdgcn_readfirstlane(tid >> 6), r32 = lane & 31, h = lane >> 5;
;     const int nunits = 16 * nN, kw = K >> 3, nk = kw >> 4;
;     for (int un = (int)blockIdx.x; un < nunits; un += (int)gridDim.x) {
;         const int rb = un & 3, wc = (un >> 2) & 3, pn = un >> 4;
;         const bf16_t* ap = A + (size_t)(MP + rb * 32 + r32) * K + w * kw + h * 8;
;         const bf16_t* b0p = Bt + (size_t)(pn * 256 + wc * 32 + r32) * K + w * kw + h * 8;
;         const bf16_t* b1p = b0p + (size_t)128 * K;
	v_pk_mul_f32 v[24:25], v[24:25], v[184:185] op_sel_hi:[1,0]
	v_exp_f32_e32 v30, v30
	v_exp_f32_e32 v31, v31
	v_exp_f32_e32 v32, v32
	v_exp_f32_e32 v33, v33
	v_exp_f32_e32 v22, v22
	v_exp_f32_e32 v23, v23
	v_exp_f32_e32 v24, v24
	v_exp_f32_e32 v25, v25
	v_pk_fma_f32 v[30:31], v[30:31], v[244:245], v[244:245] op_sel_hi:[1,0,0]
	v_pk_fma_f32 v[32:33], v[32:33], v[244:245], v[244:245] op_sel_hi:[1,0,0]
	v_pk_fma_f32 v[22:23], v[22:23], v[244:245], v[244:245] op_sel_hi:[1,0,0]
	v_pk_fma_f32 v[24:25], v[24:25], v[244:245], v[244:245] op_sel_hi:[1,0,0]
	v_rcp_f32_e32 v30, v30
	v_rcp_f32_e32 v31, v31
	v_rcp_f32_e32 v32, v32
	v_rcp_f32_e32 v33, v33
	v_rcp_f32_e32 v22, v22
	v_rcp_f32_e32 v23, v23
	v_rcp_f32_e32 v24, v24
	v_rcp_f32_e32 v25, v25
	v_pk_mul_f32 v[26:27], v[26:27], v[30:31]
	v_pk_mul_f32 v[28:29], v[28:29], v[32:33]
	v_pk_mul_f32 v[18:19], v[18:19], v[22:23]
	v_pk_mul_f32 v[20:21], v[20:21], v[24:25]
	v_cvt_pk_bf16_f32 v26, v26, v27
	v_cvt_pk_bf16_f32 v27, v28, v29
	v_cvt_pk_bf16_f32 v28, v18, v19
	v_cvt_pk_bf16_f32 v29, v20, v21
	global_store_dwordx4 v183, v[26:29], s[24:25] nt
	v_add_u32_e32 v183, 0x16000, v183
	v_pk_mul_f32 v[14:15], v[14:15], v[230:231] op_sel_hi:[1,0]
	v_pk_mul_f32 v[16:17], v[16:17], v[230:231] op_sel_hi:[1,0]
	v_pk_mul_f32 v[6:7], v[6:7], v[230:231] op_sel_hi:[1,0]
	v_pk_mul_f32 v[8:9], v[8:9], v[230:231] op_sel_hi:[1,0]
	v_exp_f32_e32 v14, v14
	v_exp_f32_e32 v15, v15
	v_exp_f32_e32 v16, v16
	v_exp_f32_e32 v17, v17
	v_exp_f32_e32 v6, v6
	v_exp_f32_e32 v7, v7
	v_exp_f32_e32 v8, v8
	v_exp_f32_e32 v9, v9
	v_pk_fma_f32 v[14:15], v[14:15], v[246:247], v[246:247] op_sel_hi:[1,0,0]
	v_pk_fma_f32 v[16:17], v[16:17], v[246:247], v[246:247] op_sel_hi:[1,0,0]
	v_pk_fma_f32 v[6:7], v[6:7], v[246:247], v[246:247] op_sel_hi:[1,0,0]
	v_pk_fma_f32 v[8:9], v[8:9], v[246:247], v[246:247] op_sel_hi:[1,0,0]
	v_rcp_f32_e32 v14, v14
	v_rcp_f32_e32 v15, v15
	v_rcp_f32_e32 v16, v16
	v_rcp_f32_e32 v17, v17
	v_rcp_f32_e32 v6, v6
	v_rcp_f32_e32 v7, v7
	v_rcp_f32_e32 v8, v8
	v_rcp_f32_e32 v9, v9
	v_pk_mul_f32 v[10:11], v[10:11], v[14:15]
	v_pk_mul_f32 v[12:13], v[12:13], v[16:17]
	v_pk_mul_f32 v[2:3], v[2:3], v[6:7]
	v_pk_mul_f32 v[4:5], v[4:5], v[8:9]
	v_cvt_pk_bf16_f32 v10, v10, v11
	v_cvt_pk_bf16_f32 v11, v12, v13
	v_cvt_pk_bf16_f32 v12, v2, v3
	v_cvt_pk_bf16_f32 v13, v4, v5
	global_store_dwordx4 v183, v[10:13], s[24:25] nt
	s_cbranch_vccnz .LBB0_1424
	s_andn2_b64 vcc, exec, s[26:27]
	s_cbranch_vccnz .LBB0_1423
	s_barrier
	s_branch .LBB0_1423
.LBB0_1434:
	s_barrier
.LBB0_1435:
	s_cmpk_gt_i32 s2, 0x15f
	v_readfirstlane_b32 s0, v162
	s_cbranch_scc1 .LBB0_1440
	v_and_b32_e32 v155, 63, v162
	v_lshrrev_b32_e32 v156, 6, v162
	v_and_b32_e32 v156, 7, v156
	v_lshlrev_b32_e32 v156, 13, v156
	v_add_u32_e32 v156, 0x10000, v156
	v_lshrrev_b32_e32 v182, 3, v155
	v_and_b32_e32 v165, 31, v155
	v_sub_u32_e32 v182, v182, v165
	v_lshlrev_b32_e32 v182, 11, v182
	v_and_b32_e32 v165, 7, v155
	v_lshrrev_b32_e32 v183, 5, v155
	v_sub_u32_e32 v165, v165, v183
	v_lshl_add_u32 v182, v165, 4, v182
	v_ashrrev_i32_e32 v183, 31, v182
	v_lshrrev_b32_e32 v194, 4, v155
	v_and_b32_e32 v194, 3, v194
	v_and_b32_e32 v165, 7, v155
	v_xor_b32_e32 v194, v194, v165
	v_lshlrev_b32_e32 v194, 4, v194
	v_lshrrev_b32_e32 v165, 3, v155
	v_lshl_add_u32 v194, v165, 7, v194
	v_add_u32_e32 v194, v156, v194
	v_xor_b32_e32 v195, 64, v194
	v_and_b32_e32 v165, 31, v155
	v_lshl_add_u32 v156, v165, 7, v156
	v_lshrrev_b32_e32 v165, 1, v155
	v_and_b32_e32 v165, 7, v165
	v_lshrrev_b32_e32 v155, 5, v155
	v_add_u32_e32 v244, 0, v155
	v_xor_b32_e32 v244, v244, v165
	v_lshl_add_u32 v244, v244, 4, v156
	v_add_u32_e32 v245, 2, v155
	v_xor_b32_e32 v245, v245, v165
	v_lshl_add_u32 v245, v245, 4, v156
	v_add_u32_e32 v246, 4, v155
	v_xor_b32_e32 v246, v246, v165
	v_lshl_add_u32 v246, v246, 4, v156
	v_add_u32_e32 v193, 6, v155
	v_xor_b32_e32 v193, v193, v165
	v_lshl_add_u32 v193, v193, 4, v156
	s_mov_b32 s80, 0x4000
	s_mov_b32 s81, 0
	s_mov_b32 s82, 0xffff4000
	s_mov_b32 s83, -1
	s_and_b32 s76, s2, 0xffffffe0
	s_and_b32 s77, s2, 7
	s_lshl_b32 s77, s77, 2
	s_or_b32 s76, s76, s77
	s_bfe_u32 s77, s2, 0x20003
	s_or_b32 s76, s76, s77
	s_and_b32 s77, s3, 31
	s_cmp_eq_u32 s77, 0
	s_cselect_b32 s76, s76, s2
	v_and_b32_e32 v1, 1, v1
	v_lshlrev_b32_e32 v34, 4, v1
	v_mov_b32_e32 v35, 0
	s_lshr_b32 s0, s0, 6
	s_mov_b32 s5, 0
	v_lshl_add_u64 v[2:3], s[34:35], 0, v[34:35]
	s_lshl_b32 s4, s0, 8
	v_lshl_add_u64 v[36:37], v[2:3], 0, s[4:5]
	v_mbcnt_lo_u32_b32 v2, -1, 0
	v_lshl_add_u64 v[4:5], s[22:23], 0, v[34:35]
	v_mbcnt_hi_u32_b32 v2, -1, v2
	v_and_b32_e32 v42, 31, v162
	v_lshl_add_u64 v[38:39], v[4:5], 0, s[4:5]
	v_and_b32_e32 v4, 64, v2
	v_lshlrev_b32_e32 v1, 10, v1
	v_lshlrev_b32_e32 v6, 2, v42
	v_xor_b32_e32 v3, 8, v2
	v_add_u32_e32 v4, 64, v4
	v_add3_u32 v7, 0, v1, v6
	v_and_b32_e32 v1, 0x3f00, v164
	s_lshl_b32 s4, s0, 13
	v_cmp_lt_i32_e64 s[0:1], v3, v4
	v_add_u32_e32 v8, 0, v1
	v_and_b32_e32 v9, 0xf0, v164
	v_and_b32_e32 v1, 8, v162
	v_and_b32_e32 v6, 28, v163
	v_cndmask_b32_e64 v2, v2, v3, s[0:1]
	v_add_u32_e32 v44, s4, v7
	v_cmp_eq_u32_e32 vcc, 0, v1
	v_lshrrev_b32_e32 v1, 4, v162
	v_lshlrev_b32_e32 v43, 2, v2
	s_lshl_b32 s8, s76, 3
	s_lshl_b32 s9, s3, 3
	s_lshl_b32 s10, s76, 5
	s_lshl_b32 s11, s3, 5
	s_mov_b32 s12, 0x40000
	v_add_u32_e32 v45, v8, v9
	v_mov_b32_e32 v46, 0x358637bd
	s_mov_b32 s13, 0x800000
	v_lshlrev_b32_e32 v40, 1, v6
	v_add_u32_e32 v47, 0x800, v44
	v_add_u32_e32 v48, 0x1000, v44
	v_add_u32_e32 v49, 0x1800, v44
	s_mov_b32 s14, s76
	s_branch .LBB0_1438

; DI u32x4 pk8(f32x4 a, f32x4 b) { u32x4 w; w.x = pk2(a[0], a[1]); w.y = pk2(a[2], a[3]); w.z = pk2(b[0], b[1]); w.w = pk2(b[2], b[3]); return w; }
; DI void unpack8(const u32x4 w, float (&f)[8]) { f[0] = bflo(w.x); f[1] = bfhi(w.x); f[2] = bflo(w.y); f[3] = bfhi(w.y); f[4] = bflo(w.z); f[5] = bfhi(w.z); f[6] = bflo(w.w); f[7] = bfhi(w.w); }
;     DI void operator()(const Acc& acc, const pg8::Unit& u, int wr, int wc, int fr, int fq) const {
;     ...
;             for (int ai = 0; ai < 2; ++ai) {
;                 u32x4 rx[4][2];
; #pragma unroll
;                 for (int m = 0; m < 4; ++m)
; #pragma unroll
;                     for (int bj = 0; bj < 2; ++bj) rx[m][bj] = *(const u32x4*)(XN + (size_t)(row0 + ai * 128 + m * 16) * D + colb + bj * 128);
; #pragma unroll
;                 for (int m = 0; m < 4; ++m) {
;                     const int row = row0 + ai * 128 + m * 16;
;                     float ssq = 0.f;
; #pragma unroll
;                     for (int bj = 0; bj < 2; ++bj) {
;                         const int col = colb + bj * 128;
;                         float f[8]; unpack8(rx[m][bj], f);
;                         const f32x4 v0 = (f32x4){f[0], f[1], f[2], f[3]} + acc[ai][bj][m][0], v1 = (f32x4){f[4], f[5], f[6], f[7]} + acc[ai][bj][m][1];
;                         if (MODE == 2) { __builtin_nontemporal_store(v0, (f32x4*)(out + (size_t)row * D + col)); __builtin_nontemporal_store(v1, (f32x4*)(out + (size_t)row * D + col + 4)); }
;                         else {
;                             ssq += (v0[0] * v0[0] + v0[1] * v0[1]) + (v0[2] * v0[2] + v0[3] * v0[3]) + (v1[0] * v1[0] + v1[1] * v1[1]) + (v1[2] * v1[2] + v1[3] * v1[3]);
;                             *(u32x4*)(XN + (size_t)row * D + col) = pk8(v0, v1);
;                         }
;                     }
.LBB0_1516:
	v_lshl_or_b32 v144, s42, 8, v157
	v_lshl_add_u32 v148, s41, 8, v155
	v_ashrrev_i32_e32 v145, 31, v144
	v_ashrrev_i32_e32 v149, 31, v148
	v_lshl_add_u64 v[146:147], v[144:145], 1, s[34:35]
	v_lshlrev_b64 v[150:151], 11, v[148:149]
	v_or_b32_e32 v182, 16, v148
	v_lshl_add_u64 v[150:151], v[146:147], 0, v[150:151]
	v_ashrrev_i32_e32 v183, 31, v182
	global_load_dwordx4 v[162:165], v[150:151], off
	global_load_dwordx4 v[166:169], v[150:151], off offset:256
	v_lshlrev_b64 v[150:151], 11, v[182:183]
	v_or_b32_e32 v194, 32, v148
	v_lshl_add_u64 v[150:151], v[146:147], 0, v[150:151]
	v_ashrrev_i32_e32 v195, 31, v194
	global_load_dwordx4 v[170:173], v[150:151], off
	global_load_dwordx4 v[174:177], v[150:151], off offset:256
	v_lshlrev_b64 v[150:151], 11, v[194:195]
	v_lshl_add_u64 v[184:185], v[146:147], 0, v[150:151]
	global_load_dwordx4 v[178:181], v[184:185], off
	v_or_b32_e32 v150, 48, v148
	v_ashrrev_i32_e32 v151, 31, v150
	v_lshlrev_b64 v[190:191], 12, v[182:183]
	global_load_dwordx4 v[182:185], v[184:185], off offset:256
	v_lshlrev_b64 v[186:187], 12, v[148:149]
	v_lshlrev_b64 v[188:189], 11, v[150:151]
	v_lshlrev_b64 v[144:145], 2, v[144:145]
	v_lshl_add_u64 v[186:187], s[74:75], 0, v[186:187]
	v_lshl_add_u64 v[192:193], v[146:147], 0, v[188:189]
	v_lshl_add_u64 v[196:197], v[186:187], 0, v[144:145]
	v_lshl_add_u64 v[198:199], s[74:75], 0, v[190:191]
	global_load_dwordx4 v[186:189], v[192:193], off
	s_nop 0
	global_load_dwordx4 v[190:193], v[192:193], off offset:256
	v_lshl_add_u64 v[198:199], v[198:199], 0, v[144:145]
	s_and_b64 vcc, exec, s[0:1]
	s_mov_b64 s[0:1], -1
	s_waitcnt vmcnt(0)
	v_lshlrev_b32_e32 v200, 16, v162
	v_and_b32_e32 v201, 0xffff0000, v162
	v_lshlrev_b32_e32 v162, 16, v163
	v_and_b32_e32 v163, 0xffff0000, v163
	v_lshlrev_b32_e32 v202, 16, v164
	v_and_b32_e32 v203, 0xffff0000, v164
	v_lshlrev_b32_e32 v164, 16, v165
	v_and_b32_e32 v165, 0xffff0000, v165
	v_lshlrev_b32_e32 v204, 16, v166
	v_and_b32_e32 v205, 0xffff0000, v166
	v_lshlrev_b32_e32 v166, 16, v167
	v_and_b32_e32 v167, 0xffff0000, v167
	v_lshlrev_b32_e32 v206, 16, v168
	v_and_b32_e32 v207, 0xffff0000, v168
	v_lshlrev_b32_e32 v168, 16, v169
	v_and_b32_e32 v169, 0xffff0000, v169
	v_pk_add_f32 v[126:127], v[126:127], v[162:163]
	v_pk_add_f32 v[122:123], v[122:123], v[164:165]
	v_pk_add_f32 v[118:119], v[118:119], v[166:167]
	v_pk_add_f32 v[114:115], v[114:115], v[168:169]
	v_lshlrev_b32_e32 v162, 16, v170
	v_and_b32_e32 v163, 0xffff0000, v170
	v_lshlrev_b32_e32 v164, 16, v171
	v_and_b32_e32 v165, 0xffff0000, v171
	v_lshlrev_b32_e32 v166, 16, v172
	v_and_b32_e32 v167, 0xffff0000, v172
	v_lshlrev_b32_e32 v168, 16, v173
	v_and_b32_e32 v169, 0xffff0000, v173
	v_lshlrev_b32_e32 v170, 16, v174
	v_and_b32_e32 v171, 0xffff0000, v174
	v_lshlrev_b32_e32 v172, 16, v175
	v_and_b32_e32 v173, 0xffff0000, v175
	v_lshlrev_b32_e32 v174, 16, v176
	v_and_b32_e32 v175, 0xffff0000, v176
	v_pk_add_f32 v[124:125], v[124:125], v[200:201]
	v_lshlrev_b32_e32 v176, 16, v177
	v_and_b32_e32 v177, 0xffff0000, v177
	v_pk_add_f32 v[110:111], v[110:111], v[164:165]
	v_pk_add_f32 v[108:109], v[108:109], v[162:163]
	v_pk_add_f32 v[92:93], v[92:93], v[174:175]
	v_pk_add_f32 v[120:121], v[120:121], v[202:203]
	v_pk_add_f32 v[116:117], v[116:117], v[204:205]
	v_pk_add_f32 v[112:113], v[112:113], v[206:207]
	global_store_dwordx4 v[196:197], v[124:127], off nt
	global_store_dwordx4 v[196:197], v[120:123], off offset:16 nt
	global_store_dwordx4 v[196:197], v[116:119], off offset:512 nt
	global_store_dwordx4 v[196:197], v[112:115], off offset:528 nt
	v_pk_add_f32 v[106:107], v[106:107], v[168:169]
	v_pk_add_f32 v[104:105], v[104:105], v[166:167]
	v_pk_add_f32 v[102:103], v[102:103], v[172:173]
	v_pk_add_f32 v[100:101], v[100:101], v[170:171]
	v_pk_add_f32 v[94:95], v[94:95], v[176:177]
	global_store_dwordx4 v[198:199], v[108:111], off nt
	global_store_dwordx4 v[198:199], v[104:107], off offset:16 nt
	global_store_dwordx4 v[198:199], v[100:103], off offset:512 nt
	global_store_dwordx4 v[198:199], v[92:95], off offset:528 nt
	s_nop 0
	v_lshlrev_b32_e32 v100, 16, v180
	v_lshlrev_b32_e32 v92, 16, v178
	v_and_b32_e32 v93, 0xffff0000, v178
	v_pk_add_f32 v[92:93], v[96:97], v[92:93]
	v_lshlrev_b64 v[96:97], 12, v[194:195]
	v_lshlrev_b32_e32 v94, 16, v179
	v_and_b32_e32 v95, 0xffff0000, v179
	v_and_b32_e32 v101, 0xffff0000, v180
	v_lshlrev_b32_e32 v102, 16, v181
	v_and_b32_e32 v103, 0xffff0000, v181
	v_lshl_add_u64 v[96:97], s[74:75], 0, v[96:97]
	v_pk_add_f32 v[94:95], v[98:99], v[94:95]
	v_pk_add_f32 v[90:91], v[90:91], v[102:103]
	v_pk_add_f32 v[88:89], v[88:89], v[100:101]
	v_lshl_add_u64 v[96:97], v[96:97], 0, v[144:145]
	global_store_dwordx4 v[96:97], v[92:95], off nt
	global_store_dwordx4 v[96:97], v[88:91], off offset:16 nt
	v_add_u32_e32 v98, 0x90, v148
	v_lshlrev_b32_e32 v92, 16, v184
	v_lshlrev_b32_e32 v88, 16, v182
	v_and_b32_e32 v89, 0xffff0000, v182
	v_lshlrev_b32_e32 v90, 16, v183
	v_and_b32_e32 v91, 0xffff0000, v183
	v_and_b32_e32 v93, 0xffff0000, v184
	v_lshlrev_b32_e32 v94, 16, v185
	v_and_b32_e32 v95, 0xffff0000, v185
	v_pk_add_f32 v[86:87], v[86:87], v[90:91]
	v_pk_add_f32 v[84:85], v[84:85], v[88:89]
	v_pk_add_f32 v[76:77], v[76:77], v[92:93]
	v_pk_add_f32 v[78:79], v[78:79], v[94:95]
	global_store_dwordx4 v[96:97], v[84:87], off offset:512 nt
	global_store_dwordx4 v[96:97], v[76:79], off offset:528 nt
	v_add_u32_e32 v96, 0x80, v148
	v_lshlrev_b32_e32 v84, 16, v188
	v_lshlrev_b32_e32 v76, 16, v186
	v_and_b32_e32 v77, 0xffff0000, v186
	v_pk_add_f32 v[76:77], v[80:81], v[76:77]
	v_lshlrev_b64 v[80:81], 12, v[150:151]
	v_lshlrev_b32_e32 v78, 16, v187
	v_and_b32_e32 v79, 0xffff0000, v187
; DI u32x4 pk8(f32x4 a, f32x4 b) { u32x4 w; w.x = pk2(a[0], a[1]); w.y = pk2(a[2], a[3]); w.z = pk2(b[0], b[1]); w.w = pk2(b[2], b[3]); return w; }
; DI void unpack8(const u32x4 w, float (&f)[8]) { f[0] = bflo(w.x); f[1] = bfhi(w.x); f[2] = bflo(w.y); f[3] = bfhi(w.y); f[4] = bflo(w.z); f[5] = bfhi(w.z); f[6] = bflo(w.w); f[7] = bfhi(w.w); }
;     DI void operator()(const Acc& acc, const pg8::Unit& u, int wr, int wc, int fr, int fq) const {
;     ...
;             for (int ai = 0; ai < 2; ++ai) {
;                 u32x4 rx[4][2];
; #pragma unroll
;                 for (int m = 0; m < 4; ++m)
; #pragma unroll
;                     for (int bj = 0; bj < 2; ++bj) rx[m][bj] = *(const u32x4*)(XN + (size_t)(row0 + ai * 128 + m * 16) * D + colb + bj * 128);
; #pragma unroll
;                 for (int m = 0; m < 4; ++m) {
;                     const int row = row0 + ai * 128 + m * 16;
;                     float ssq = 0.f;
; #pragma unroll
;                     for (int bj = 0; bj < 2; ++bj) {
;                         const int col = colb + bj * 128;
;                         float f[8]; unpack8(rx[m][bj], f);
;                         const f32x4 v0 = (f32x4){f[0], f[1], f[2], f[3]} + acc[ai][bj][m][0], v1 = (f32x4){f[4], f[5], f[6], f[7]} + acc[ai][bj][m][1];
;                         if (MODE == 2) { __builtin_nontemporal_store(v0, (f32x4*)(out + (size_t)row * D + col)); __builtin_nontemporal_store(v1, (f32x4*)(out + (size_t)row * D + col + 4)); }
;                         else {
;                             ssq += (v0[0] * v0[0] + v0[1] * v0[1]) + (v0[2] * v0[2] + v0[3] * v0[3]) + (v1[0] * v1[0] + v1[1] * v1[1]) + (v1[2] * v1[2] + v1[3] * v1[3]);
;                             *(u32x4*)(XN + (size_t)row * D + col) = pk8(v0, v1);
;                         }
;                     }
	v_and_b32_e32 v85, 0xffff0000, v188
	v_lshlrev_b32_e32 v86, 16, v189
	v_and_b32_e32 v87, 0xffff0000, v189
	v_lshl_add_u64 v[80:81], s[74:75], 0, v[80:81]
	v_pk_add_f32 v[78:79], v[82:83], v[78:79]
	v_pk_add_f32 v[74:75], v[74:75], v[86:87]
	v_pk_add_f32 v[72:73], v[72:73], v[84:85]
	v_lshl_add_u64 v[80:81], v[80:81], 0, v[144:145]
	global_store_dwordx4 v[80:81], v[76:79], off nt
	global_store_dwordx4 v[80:81], v[72:75], off offset:16 nt
	v_ashrrev_i32_e32 v97, 31, v96
	v_lshlrev_b32_e32 v76, 16, v192
	v_lshlrev_b32_e32 v72, 16, v190
	v_and_b32_e32 v73, 0xffff0000, v190
	v_lshlrev_b32_e32 v74, 16, v191
	v_and_b32_e32 v75, 0xffff0000, v191
	v_and_b32_e32 v77, 0xffff0000, v192
	v_lshlrev_b32_e32 v78, 16, v193
	v_and_b32_e32 v79, 0xffff0000, v193
	v_pk_add_f32 v[70:71], v[70:71], v[74:75]
	v_pk_add_f32 v[68:69], v[68:69], v[72:73]
	v_pk_add_f32 v[64:65], v[64:65], v[76:77]
	v_pk_add_f32 v[66:67], v[66:67], v[78:79]
	global_store_dwordx4 v[80:81], v[68:71], off offset:512 nt
	global_store_dwordx4 v[80:81], v[64:67], off offset:528 nt
	v_ashrrev_i32_e32 v99, 31, v98
	v_add_u32_e32 v100, 0xa0, v148
	v_lshlrev_b64 v[64:65], 11, v[96:97]
	v_lshl_add_u64 v[64:65], v[146:147], 0, v[64:65]
	global_load_dwordx4 v[68:71], v[64:65], off
	global_load_dwordx4 v[72:75], v[64:65], off offset:256
	v_lshlrev_b64 v[64:65], 11, v[98:99]
	v_lshl_add_u64 v[64:65], v[146:147], 0, v[64:65]
	global_load_dwordx4 v[76:79], v[64:65], off
	global_load_dwordx4 v[80:83], v[64:65], off offset:256
	v_ashrrev_i32_e32 v101, 31, v100
	v_lshlrev_b64 v[64:65], 11, v[100:101]
	v_lshl_add_u64 v[64:65], v[146:147], 0, v[64:65]
	global_load_dwordx4 v[84:87], v[64:65], off
	global_load_dwordx4 v[88:91], v[64:65], off offset:256
	v_add_u32_e32 v102, 0xb0, v148
	v_ashrrev_i32_e32 v103, 31, v102
	v_lshlrev_b64 v[64:65], 11, v[102:103]
	v_lshl_add_u64 v[64:65], v[146:147], 0, v[64:65]
	global_load_dwordx4 v[92:95], v[64:65], off
	s_nop 0
	global_load_dwordx4 v[64:67], v[64:65], off offset:256
	s_waitcnt vmcnt(7)
	v_lshlrev_b32_e32 v104, 16, v68
	v_and_b32_e32 v105, 0xffff0000, v68
	v_lshlrev_b32_e32 v68, 16, v69
	v_and_b32_e32 v69, 0xffff0000, v69
	v_pk_add_f32 v[62:63], v[62:63], v[68:69]
	v_lshlrev_b64 v[68:69], 12, v[96:97]
	v_lshlrev_b32_e32 v106, 16, v70
	v_and_b32_e32 v107, 0xffff0000, v70
	v_lshlrev_b32_e32 v70, 16, v71
	v_and_b32_e32 v71, 0xffff0000, v71
	v_lshl_add_u64 v[68:69], s[74:75], 0, v[68:69]
	v_pk_add_f32 v[60:61], v[60:61], v[104:105]
	v_pk_add_f32 v[58:59], v[58:59], v[70:71]
	v_pk_add_f32 v[56:57], v[56:57], v[106:107]
	v_lshl_add_u64 v[68:69], v[68:69], 0, v[144:145]
	global_store_dwordx4 v[68:69], v[60:63], off nt
	global_store_dwordx4 v[68:69], v[56:59], off offset:16 nt
	s_waitcnt vmcnt(8)
	v_lshlrev_b32_e32 v60, 16, v74
	v_lshlrev_b32_e32 v56, 16, v72
	v_and_b32_e32 v57, 0xffff0000, v72
	v_lshlrev_b32_e32 v58, 16, v73
	v_and_b32_e32 v59, 0xffff0000, v73
	v_and_b32_e32 v61, 0xffff0000, v74
	v_lshlrev_b32_e32 v62, 16, v75
	v_and_b32_e32 v63, 0xffff0000, v75
	v_pk_add_f32 v[54:55], v[54:55], v[58:59]
	v_pk_add_f32 v[52:53], v[52:53], v[56:57]
	v_pk_add_f32 v[44:45], v[44:45], v[60:61]
	v_pk_add_f32 v[46:47], v[46:47], v[62:63]
	global_store_dwordx4 v[68:69], v[52:55], off offset:512 nt
	global_store_dwordx4 v[68:69], v[44:47], off offset:528 nt
	s_waitcnt vmcnt(9)
	v_lshlrev_b32_e32 v52, 16, v78
	v_lshlrev_b32_e32 v44, 16, v76
	v_and_b32_e32 v45, 0xffff0000, v76
	v_pk_add_f32 v[44:45], v[48:49], v[44:45]
	v_lshlrev_b64 v[48:49], 12, v[98:99]
	v_lshlrev_b32_e32 v46, 16, v77
	v_and_b32_e32 v47, 0xffff0000, v77
	v_and_b32_e32 v53, 0xffff0000, v78
	v_lshlrev_b32_e32 v54, 16, v79
	v_and_b32_e32 v55, 0xffff0000, v79
	v_lshl_add_u64 v[48:49], s[74:75], 0, v[48:49]
	v_pk_add_f32 v[46:47], v[50:51], v[46:47]
	v_pk_add_f32 v[42:43], v[42:43], v[54:55]
	v_pk_add_f32 v[40:41], v[40:41], v[52:53]
	v_lshl_add_u64 v[48:49], v[48:49], 0, v[144:145]
	global_store_dwordx4 v[48:49], v[44:47], off nt
	global_store_dwordx4 v[48:49], v[40:43], off offset:16 nt
	s_waitcnt vmcnt(10)
	v_lshlrev_b32_e32 v44, 16, v82
	v_lshlrev_b32_e32 v40, 16, v80
	v_and_b32_e32 v41, 0xffff0000, v80
	v_lshlrev_b32_e32 v42, 16, v81
	v_and_b32_e32 v43, 0xffff0000, v81
	v_and_b32_e32 v45, 0xffff0000, v82
	v_lshlrev_b32_e32 v46, 16, v83
	v_and_b32_e32 v47, 0xffff0000, v83
	v_pk_add_f32 v[38:39], v[38:39], v[42:43]
	v_pk_add_f32 v[36:37], v[36:37], v[40:41]
	v_pk_add_f32 v[28:29], v[28:29], v[44:45]
	v_pk_add_f32 v[30:31], v[30:31], v[46:47]
	global_store_dwordx4 v[48:49], v[36:39], off offset:512 nt
	global_store_dwordx4 v[48:49], v[28:31], off offset:528 nt
	s_waitcnt vmcnt(11)
; #define PG8_BAR __builtin_amdgcn_s_barrier()
; template <class Epi, bool ALIGN_EPI>
; __device__ __forceinline__ void gemm_phase(LAS unsigned char* lds, const Gemm g, const StaticOrder& S, const Epi& E) {
;     ...
;     PG8_WAIT_V(0);
;     if constexpr (!ALIGN_EPI) { if (wr == 0) PG8_BAR; }
;     PG8_BAR;
;     DI void operator()(const Acc& acc, const pg8::Unit& u, int wr, int wc, int fr, int fq) const {
;     ...
;             for (int ai = 0; ai < 2; ++ai) {
;                 u32x4 rx[4][2];
; #pragma unroll
;                 for (int m = 0; m < 4; ++m)
; #pragma unroll
;                     for (int bj = 0; bj < 2; ++bj) rx[m][bj] = *(const u32x4*)(XN + (size_t)(row0 + ai * 128 + m * 16) * D + colb + bj * 128);
; #pragma unroll
;                 for (int m = 0; m < 4; ++m) {
;                     const int row = row0 + ai * 128 + m * 16;
;                     float ssq = 0.f;
; #pragma unroll
;                     for (int bj = 0; bj < 2; ++bj) {
;                         const int col = colb + bj * 128;
;                         float f[8]; unpack8(rx[m][bj], f);
;                         const f32x4 v0 = (f32x4){f[0], f[1], f[2], f[3]} + acc[ai][bj][m][0], v1 = (f32x4){f[4], f[5], f[6], f[7]} + acc[ai][bj][m][1];
;                         if (MODE == 2) { __builtin_nontemporal_store(v0, (f32x4*)(out + (size_t)row * D + col)); __builtin_nontemporal_store(v1, (f32x4*)(out + (size_t)row * D + col + 4)); }
;                         else {
;                             ssq += (v0[0] * v0[0] + v0[1] * v0[1]) + (v0[2] * v0[2] + v0[3] * v0[3]) + (v1[0] * v1[0] + v1[1] * v1[1]) + (v1[2] * v1[2] + v1[3] * v1[3]);
;                             *(u32x4*)(XN + (size_t)row * D + col) = pk8(v0, v1);
;                         }
;                     }
; template <class EpiS>
; DI void sample_gemm(LAS unsigned char* lds, const bf16_t* A, const bf16_t* Bt, int nN, int K, const EpiS& E) {
;     const int tid = threadIdx.x, lane = tid & 63, w = __builtin_amdgcn_readfirstlane(tid >> 6), r32 = lane & 31, h = lane >> 5;
;     const int nunits = 16 * nN, kw = K >> 3, nk = kw >> 4;
;     for (int un = (int)blockIdx.x; un < nunits; un += (int)gridDim.x) {
;         const int rb = un & 3, wc = (un >> 2) & 3, pn = un >> 4;
;         const bf16_t* ap = A + (size_t)(MP + rb * 32 + r32) * K + w * kw + h * 8;
;         const bf16_t* b0p = Bt + (size_t)(pn * 256 + wc * 32 + r32) * K + w * kw + h * 8;
	v_lshlrev_b32_e32 v36, 16, v86
	v_lshlrev_b32_e32 v28, 16, v84
	v_and_b32_e32 v29, 0xffff0000, v84
	v_pk_add_f32 v[28:29], v[32:33], v[28:29]
	v_lshlrev_b64 v[32:33], 12, v[100:101]
	v_lshlrev_b32_e32 v30, 16, v85
	v_and_b32_e32 v31, 0xffff0000, v85
	v_and_b32_e32 v37, 0xffff0000, v86
	v_lshlrev_b32_e32 v38, 16, v87
	v_and_b32_e32 v39, 0xffff0000, v87
	v_lshl_add_u64 v[32:33], s[74:75], 0, v[32:33]
	v_pk_add_f32 v[30:31], v[34:35], v[30:31]
	v_pk_add_f32 v[26:27], v[26:27], v[38:39]
	v_pk_add_f32 v[24:25], v[24:25], v[36:37]
	v_lshl_add_u64 v[32:33], v[32:33], 0, v[144:145]
	global_store_dwordx4 v[32:33], v[28:31], off nt
	global_store_dwordx4 v[32:33], v[24:27], off offset:16 nt
	s_waitcnt vmcnt(12)
	v_lshlrev_b32_e32 v28, 16, v90
	v_lshlrev_b32_e32 v24, 16, v88
	v_and_b32_e32 v25, 0xffff0000, v88
	v_lshlrev_b32_e32 v26, 16, v89
	v_and_b32_e32 v27, 0xffff0000, v89
	v_and_b32_e32 v29, 0xffff0000, v90
	v_lshlrev_b32_e32 v30, 16, v91
	v_and_b32_e32 v31, 0xffff0000, v91
	v_pk_add_f32 v[22:23], v[22:23], v[26:27]
	v_pk_add_f32 v[20:21], v[20:21], v[24:25]
	v_pk_add_f32 v[12:13], v[12:13], v[28:29]
	v_pk_add_f32 v[14:15], v[14:15], v[30:31]
	global_store_dwordx4 v[32:33], v[20:23], off offset:512 nt
	global_store_dwordx4 v[32:33], v[12:15], off offset:528 nt
	s_waitcnt vmcnt(13)
	v_lshlrev_b32_e32 v20, 16, v94
	v_lshlrev_b32_e32 v12, 16, v92
	v_and_b32_e32 v13, 0xffff0000, v92
	v_pk_add_f32 v[12:13], v[16:17], v[12:13]
	v_lshlrev_b64 v[16:17], 12, v[102:103]
	v_lshlrev_b32_e32 v14, 16, v93
	v_and_b32_e32 v15, 0xffff0000, v93
	v_and_b32_e32 v21, 0xffff0000, v94
	v_lshlrev_b32_e32 v22, 16, v95
	v_and_b32_e32 v23, 0xffff0000, v95
	v_lshl_add_u64 v[16:17], s[74:75], 0, v[16:17]
	v_pk_add_f32 v[14:15], v[18:19], v[14:15]
	v_pk_add_f32 v[10:11], v[10:11], v[22:23]
	v_pk_add_f32 v[8:9], v[8:9], v[20:21]
	v_lshl_add_u64 v[16:17], v[16:17], 0, v[144:145]
	global_store_dwordx4 v[16:17], v[12:15], off nt
	global_store_dwordx4 v[16:17], v[8:11], off offset:16 nt
	s_waitcnt vmcnt(14)
	v_lshlrev_b32_e32 v12, 16, v66
	v_lshlrev_b32_e32 v8, 16, v64
	v_and_b32_e32 v9, 0xffff0000, v64
	v_lshlrev_b32_e32 v10, 16, v65
	v_and_b32_e32 v11, 0xffff0000, v65
	v_and_b32_e32 v13, 0xffff0000, v66
	v_lshlrev_b32_e32 v14, 16, v67
	v_and_b32_e32 v15, 0xffff0000, v67
	v_pk_add_f32 v[6:7], v[6:7], v[10:11]
	v_pk_add_f32 v[4:5], v[4:5], v[8:9]
	v_pk_add_f32 v[2:3], v[2:3], v[14:15]
	v_pk_add_f32 v[0:1], v[0:1], v[12:13]
	global_store_dwordx4 v[16:17], v[4:7], off offset:512 nt
	global_store_dwordx4 v[16:17], v[0:3], off offset:528 nt
	s_cbranch_vccnz .LBB0_1501
	s_andn2_b64 vcc, exec, s[6:7]
	s_cbranch_vccnz .LBB0_1500
	s_barrier
	s_branch .LBB0_1500
.LBB0_1519:
	s_barrier
.LBB0_1520:
	s_cmp_gt_i32 s2, 63
	v_readfirstlane_b32 s0, v153
	s_cbranch_scc1 .LBB0_1523
	v_and_b32_e32 v155, 63, v153
	v_lshrrev_b32_e32 v156, 6, v153
	v_and_b32_e32 v156, 7, v156
	v_lshlrev_b32_e32 v156, 13, v156
	v_add_u32_e32 v156, 0x10000, v156
	v_lshrrev_b32_e32 v182, 2, v155
	v_and_b32_e32 v165, 31, v155
	v_sub_u32_e32 v182, v182, v165
	v_mul_i32_i24_e32 v182, 0x1600, v182
	v_and_b32_e32 v165, 3, v155
	v_lshrrev_b32_e32 v183, 5, v155
	v_sub_u32_e32 v165, v165, v183
	v_lshl_add_u32 v182, v165, 4, v182
	v_ashrrev_i32_e32 v183, 31, v182
	v_lshrrev_b32_e32 v194, 4, v155
	v_xor_b32_e32 v194, v194, v155
	v_and_b32_e32 v194, 3, v194
	v_lshlrev_b32_e32 v194, 4, v194
	v_lshrrev_b32_e32 v165, 2, v155
	v_lshl_add_u32 v194, v165, 6, v194
	v_add_u32_e32 v194, v156, v194
	v_and_b32_e32 v165, 31, v155
	v_lshl_add_u32 v156, v165, 6, v156
	v_lshrrev_b32_e32 v165, 2, v155
	v_and_b32_e32 v165, 3, v165
	v_lshrrev_b32_e32 v155, 5, v155
	v_add_u32_e32 v244, 0, v155
	v_xor_b32_e32 v244, v244, v165
	v_lshl_add_u32 v244, v244, 4, v156
	v_add_u32_e32 v245, 2, v155
	v_xor_b32_e32 v245, v245, v165
	v_lshl_add_u32 v245, v245, 4, v156
	s_mov_b32 s80, 0x16000
	s_mov_b32 s81, 0
	s_and_b32 s76, s2, 0xffffffe0
	s_and_b32 s77, s2, 7
	s_lshl_b32 s77, s77, 2
	s_or_b32 s76, s76, s77
	s_bfe_u32 s77, s2, 0x20003
	s_or_b32 s76, s76, s77
	s_and_b32 s77, s3, 31
	s_cmp_eq_u32 s77, 0
	s_cselect_b32 s76, s76, s2
	s_mov_b32 s2, s76
	s_lshr_b32 s6, s0, 6
	s_mul_i32 s0, s6, 0x160
	s_mov_b32 s1, 0
	s_lshl_b64 s[0:1], s[0:1], 1
	s_add_u32 s4, s24, s0
	s_addc_u32 s5, s25, s1
	v_bfe_u32 v0, v153, 5, 1
	s_add_u32 s0, s20, s0
	v_lshlrev_b32_e32 v32, 4, v0
	v_mov_b32_e32 v33, 0
	s_addc_u32 s1, s21, s1
	v_and_b32_e32 v38, 31, v153
	v_lshl_add_u64 v[36:37], s[0:1], 0, v[32:33]
	s_lshl_b32 s0, s6, 13
	s_add_i32 s0, s0, 0
	v_lshlrev_b32_e32 v0, 10, v0
	v_lshlrev_b32_e32 v1, 2, v38
	v_add3_u32 v39, s0, v0, v1
	v_and_b32_e32 v0, 0x3f00, v152
	v_add_u32_e32 v0, 0, v0
	v_and_b32_e32 v1, 0xf0, v152
	v_and_b32_e32 v2, 28, v154
	s_movk_i32 s0, 0x80
	v_lshl_add_u64 v[34:35], s[4:5], 0, v[32:33]
	v_lshrrev_b32_e32 v40, 4, v153
	v_and_or_b32 v41, v152, s0, v2
	s_lshl_b32 s0, s76, 3
	s_lshl_b32 s1, s3, 3
	s_lshl_b32 s4, s76, 4
	s_lshl_b32 s5, s3, 4
	s_lshl_b32 s6, s76, 5
	s_lshl_b32 s7, s3, 5
	s_movk_i32 s8, 0x1600
	s_mov_b32 s9, 0xb0000
	v_add_u32_e32 v42, v0, v1
	v_add_u32_e32 v43, 0x800, v39
	v_add_u32_e32 v44, 0x1000, v39
	v_add_u32_e32 v45, 0x1800, v39
